# as v40 plus EpiRes epilogues (down / ev-out / od-out GEMMs): the single vmcnt(0) after the 16 hoisted residual loads replaced by counted waits vmcnt(15) before each quad's first use
# speedup vs baseline: 1.0064x; 1.0064x over previous
; __device__ __forceinline__ unsigned cvt_pk_bf16(float lo, float hi) { unsigned r; asm volatile("v_cvt_pk_bf16_f32 %0, %1, %2" : "=v"(r) : "v"(lo), "v"(hi)); return r; }
; __device__ __forceinline__ float bf_lo(unsigned w) { return __uint_as_float(w << 16); }
; __device__ __forceinline__ float bf_hi(unsigned w) { return __uint_as_float(w & 0xffff0000u); }
;     __device__ __forceinline__ void operator()(const f32x4 (&acc)[2][2][4][2], const Unit& u, int wr, int wc, int fr, int fq, const float (&rs)[2][4]) const {
;     ...
;         const int row0 = u.pm * BM + wr * 64 + fr, col0 = u.pn * BM + wc * 32 + 8 * fq;
; #pragma unroll
;         for (int ai = 0; ai < 2; ++ai) {
; #pragma unroll
;             for (int m = 0; m < 4; ++m) { bf16_t* rowp = X + (size_t)(row0 + ai * HALF + m * 16) * DM + col0; float ss = 0.f;
; #pragma unroll
;                 for (int bj = 0; bj < 2; ++bj) { const u32x4 bw = *(const u32x4*)(rowp + bj * HALF); const f32x4 a0 = acc[ai][bj][m][0], a1 = acc[ai][bj][m][1];
;                     u32x4 w; w.x = cvt_pk_bf16(bf_lo(bw.x) + alpha * a0[0], bf_hi(bw.x) + alpha * a0[1]); w.y = cvt_pk_bf16(bf_lo(bw.y) + alpha * a0[2], bf_hi(bw.y) + alpha * a0[3]);
;                     w.z = cvt_pk_bf16(bf_lo(bw.z) + alpha * a1[0], bf_hi(bw.z) + alpha * a1[1]); w.w = cvt_pk_bf16(bf_lo(bw.w) + alpha * a1[2], bf_hi(bw.w) + alpha * a1[3]);
;                     *(u32x4*)(rowp + bj * HALF) = w;
;                     ss += (bf_lo(w.x) * bf_lo(w.x) + bf_hi(w.x) * bf_hi(w.x)) + (bf_lo(w.y) * bf_lo(w.y) + bf_hi(w.y) * bf_hi(w.y));
;                     ss += (bf_lo(w.z) * bf_lo(w.z) + bf_hi(w.z) * bf_hi(w.z)) + (bf_lo(w.w) * bf_lo(w.w) + bf_hi(w.w) * bf_hi(w.w)); }
;                 ss = fq_sum(ss);
;                 if (fq == 0) part[(size_t)(row0 + ai * HALF + m * 16) * 16 + u.pn * 4 + wc] = ss; } }
.LBB0_731:
	s_lshl_b32 s0, s27, 8
	v_mov_b32_e32 v130, v151
	v_mov_b32_e32 v131, v150
	s_add_i32 s0, s0, s71
	s_lshl_b32 s48, s26, 2
	v_add_u32_e32 v148, s0, v130
	s_lshl_b32 s0, s26, 8
	s_or_b32 s0, s0, s72
	v_ashrrev_i32_e32 v149, 31, v148
	v_lshl_add_u32 v146, v131, 3, s0
	v_lshlrev_b64 v[154:155], 11, v[148:149]
	v_ashrrev_i32_e32 v147, 31, v146
	v_lshl_add_u64 v[154:155], s[94:95], 0, v[154:155]
	v_lshl_add_u64 v[158:159], v[146:147], 1, v[154:155]
	global_load_dwordx4 v[182:185], v[158:159], off
	global_load_dwordx4 v[186:189], v[158:159], off offset:256
	v_add_u32_e32 v246, 16, v148
	v_ashrrev_i32_e32 v247, 31, v246
	v_lshlrev_b64 v[246:247], 11, v[246:247]
	v_lshl_add_u64 v[246:247], s[94:95], 0, v[246:247]
	v_lshl_add_u64 v[246:247], v[146:147], 1, v[246:247]
	global_load_dwordx4 v[190:193], v[246:247], off
	global_load_dwordx4 v[194:197], v[246:247], off offset:256
	v_add_u32_e32 v248, 32, v148
	v_ashrrev_i32_e32 v249, 31, v248
	v_lshlrev_b64 v[248:249], 11, v[248:249]
	v_lshl_add_u64 v[248:249], s[94:95], 0, v[248:249]
	v_lshl_add_u64 v[248:249], v[146:147], 1, v[248:249]
	global_load_dwordx4 v[198:201], v[248:249], off
	global_load_dwordx4 v[202:205], v[248:249], off offset:256
	v_add_u32_e32 v246, 48, v148
	v_ashrrev_i32_e32 v247, 31, v246
	v_lshlrev_b64 v[246:247], 11, v[246:247]
	v_lshl_add_u64 v[246:247], s[94:95], 0, v[246:247]
	v_lshl_add_u64 v[246:247], v[146:147], 1, v[246:247]
	global_load_dwordx4 v[206:209], v[246:247], off
	global_load_dwordx4 v[210:213], v[246:247], off offset:256
	v_add_u32_e32 v248, 0x80, v148
	v_ashrrev_i32_e32 v249, 31, v248
	v_lshlrev_b64 v[248:249], 11, v[248:249]
	v_lshl_add_u64 v[248:249], s[94:95], 0, v[248:249]
	v_lshl_add_u64 v[248:249], v[146:147], 1, v[248:249]
	global_load_dwordx4 v[214:217], v[248:249], off
	global_load_dwordx4 v[218:221], v[248:249], off offset:256
	v_add_u32_e32 v246, 0x90, v148
	v_ashrrev_i32_e32 v247, 31, v246
	v_lshlrev_b64 v[246:247], 11, v[246:247]
	v_lshl_add_u64 v[246:247], s[94:95], 0, v[246:247]
	v_lshl_add_u64 v[246:247], v[146:147], 1, v[246:247]
	global_load_dwordx4 v[222:225], v[246:247], off
	global_load_dwordx4 v[226:229], v[246:247], off offset:256
	v_add_u32_e32 v248, 0xa0, v148
	v_ashrrev_i32_e32 v249, 31, v248
	v_lshlrev_b64 v[248:249], 11, v[248:249]
	v_lshl_add_u64 v[248:249], s[94:95], 0, v[248:249]
	v_lshl_add_u64 v[248:249], v[146:147], 1, v[248:249]
	global_load_dwordx4 v[230:233], v[248:249], off
	global_load_dwordx4 v[234:237], v[248:249], off offset:256
	v_add_u32_e32 v246, 0xb0, v148
	v_ashrrev_i32_e32 v247, 31, v246
	v_lshlrev_b64 v[246:247], 11, v[246:247]
	v_lshl_add_u64 v[246:247], s[94:95], 0, v[246:247]
	v_lshl_add_u64 v[246:247], v[146:147], 1, v[246:247]
	global_load_dwordx4 v[238:241], v[246:247], off
	global_load_dwordx4 v[242:245], v[246:247], off offset:256
	s_ashr_i32 s49, s48, 31
	v_cmp_eq_u32_e32 vcc, 0, v131
	s_waitcnt vmcnt(15)
	v_lshlrev_b32_e32 v130, 16, v182
	v_and_b32_e32 v134, 0xffff0000, v182
	v_lshlrev_b32_e32 v135, 16, v183
	v_and_b32_e32 v154, 0xffff0000, v183
	v_lshlrev_b32_e32 v155, 16, v184
	v_and_b32_e32 v156, 0xffff0000, v184
	v_lshlrev_b32_e32 v160, 16, v185
	v_and_b32_e32 v157, 0xffff0000, v185
	v_fmac_f32_e32 v130, 0.5, v126
	v_fmac_f32_e32 v134, 0.5, v127
	v_fmac_f32_e32 v135, 0.5, v128
	v_fmac_f32_e32 v154, 0.5, v129
	v_fmac_f32_e32 v155, 0.5, v122
	v_fmac_f32_e32 v156, 0.5, v123
	v_fmac_f32_e32 v160, 0.5, v124
	v_fmac_f32_e32 v157, 0.5, v125
	v_cvt_pk_bf16_f32 v122, v130, v134
	v_cvt_pk_bf16_f32 v123, v135, v154
	v_cvt_pk_bf16_f32 v124, v155, v156
	v_cvt_pk_bf16_f32 v125, v160, v157
	s_nop 0
	v_lshlrev_b32_e32 v130, 16, v122
	global_store_dwordx4 v[158:159], v[122:125], off
	v_lshlrev_b32_e32 v134, 16, v123
	v_lshlrev_b32_e32 v135, 16, v124
	v_and_b32_e32 v122, 0xffff0000, v122
	v_and_b32_e32 v123, 0xffff0000, v123
	v_and_b32_e32 v124, 0xffff0000, v124
	v_lshlrev_b32_e32 v154, 16, v125
	v_and_b32_e32 v125, 0xffff0000, v125
	v_mul_f32_e32 v122, v122, v122
	v_mul_f32_e32 v123, v123, v123
	v_mul_f32_e32 v124, v124, v124
	v_mul_f32_e32 v125, v125, v125
	v_fmac_f32_e32 v122, v130, v130
	v_fmac_f32_e32 v123, v134, v134
	v_fmac_f32_e32 v124, v135, v135
	v_fmac_f32_e32 v125, v154, v154
	v_add_f32_e32 v122, v122, v123
	v_add_f32_e32 v123, v124, v125
	v_add_f32_e32 v122, v122, v123
	s_waitcnt vmcnt(15)
	v_lshlrev_b32_e32 v123, 16, v186
	v_and_b32_e32 v124, 0xffff0000, v186
	v_lshlrev_b32_e32 v125, 16, v187
	v_and_b32_e32 v126, 0xffff0000, v187
	v_lshlrev_b32_e32 v127, 16, v188
	v_and_b32_e32 v128, 0xffff0000, v188
	v_lshlrev_b32_e32 v130, 16, v189
	v_and_b32_e32 v129, 0xffff0000, v189
	v_fmac_f32_e32 v123, 0.5, v118
	v_fmac_f32_e32 v124, 0.5, v119
	v_fmac_f32_e32 v125, 0.5, v120
	v_fmac_f32_e32 v126, 0.5, v121
	v_fmac_f32_e32 v127, 0.5, v114
	v_fmac_f32_e32 v128, 0.5, v115
	v_cvt_pk_bf16_f32 v114, v123, v124
	v_cvt_pk_bf16_f32 v115, v125, v126
	v_fmac_f32_e32 v130, 0.5, v116
	v_and_b32_e32 v119, 0xffff0000, v114
	v_and_b32_e32 v121, 0xffff0000, v115
	v_fmac_f32_e32 v129, 0.5, v117
	v_cvt_pk_bf16_f32 v116, v127, v128
	v_cvt_pk_bf16_f32 v117, v130, v129
	v_lshlrev_b32_e32 v118, 16, v114
	v_lshlrev_b32_e32 v120, 16, v115
	v_and_b32_e32 v124, 0xffff0000, v116
	v_and_b32_e32 v126, 0xffff0000, v117
	v_mul_f32_e32 v119, v119, v119
	v_mul_f32_e32 v121, v121, v121
	v_lshlrev_b32_e32 v123, 16, v116
	v_lshlrev_b32_e32 v125, 16, v117
	v_mul_f32_e32 v124, v124, v124
	v_mul_f32_e32 v126, v126, v126
	v_fmac_f32_e32 v119, v118, v118
	v_fmac_f32_e32 v121, v120, v120
	v_fmac_f32_e32 v124, v123, v123
	v_fmac_f32_e32 v126, v125, v125
	v_add_f32_e32 v118, v119, v121
	v_add_f32_e32 v119, v124, v126
	v_add_f32_e32 v118, v122, v118
	v_add_f32_e32 v118, v118, v119
	ds_swizzle_b32 v119, v118 offset:swizzle(SWAP,16)
	global_store_dwordx4 v[158:159], v[114:117], off offset:256
	s_waitcnt lgkmcnt(0)
	s_nop 0
	v_add_f32_e32 v114, v118, v119
	v_mov_b32_e32 v115, v114
	s_nop 1
	v_permlane32_swap_b32_e32 v114, v115
	s_and_saveexec_b64 s[50:51], vcc
	s_cbranch_execz .LBB0_733
	v_lshlrev_b64 v[116:117], 6, v[148:149]
	v_lshl_add_u64 v[116:117], s[96:97], 0, v[116:117]
	v_lshl_add_u64 v[116:117], s[48:49], 2, v[116:117]
	s_lshl_b32 s58, s70, 2
	v_lshl_add_u64 v[116:117], v[116:117], 0, s[58:59]
	v_add_f32_e32 v114, v114, v115
	global_store_dword v[116:117], v114, off
; __device__ __forceinline__ unsigned cvt_pk_bf16(float lo, float hi) { unsigned r; asm volatile("v_cvt_pk_bf16_f32 %0, %1, %2" : "=v"(r) : "v"(lo), "v"(hi)); return r; }
; __device__ __forceinline__ float bf_lo(unsigned w) { return __uint_as_float(w << 16); }
; __device__ __forceinline__ float bf_hi(unsigned w) { return __uint_as_float(w & 0xffff0000u); }
;     __device__ __forceinline__ void operator()(const f32x4 (&acc)[2][2][4][2], const Unit& u, int wr, int wc, int fr, int fq, const float (&rs)[2][4]) const {
;     ...
;             for (int m = 0; m < 4; ++m) { bf16_t* rowp = X + (size_t)(row0 + ai * HALF + m * 16) * DM + col0; float ss = 0.f;
; #pragma unroll
;                 for (int bj = 0; bj < 2; ++bj) { const u32x4 bw = *(const u32x4*)(rowp + bj * HALF); const f32x4 a0 = acc[ai][bj][m][0], a1 = acc[ai][bj][m][1];
;                     u32x4 w; w.x = cvt_pk_bf16(bf_lo(bw.x) + alpha * a0[0], bf_hi(bw.x) + alpha * a0[1]); w.y = cvt_pk_bf16(bf_lo(bw.y) + alpha * a0[2], bf_hi(bw.y) + alpha * a0[3]);
;                     w.z = cvt_pk_bf16(bf_lo(bw.z) + alpha * a1[0], bf_hi(bw.z) + alpha * a1[1]); w.w = cvt_pk_bf16(bf_lo(bw.w) + alpha * a1[2], bf_hi(bw.w) + alpha * a1[3]);
;                     *(u32x4*)(rowp + bj * HALF) = w;
;                     ss += (bf_lo(w.x) * bf_lo(w.x) + bf_hi(w.x) * bf_hi(w.x)) + (bf_lo(w.y) * bf_lo(w.y) + bf_hi(w.y) * bf_hi(w.y));
;                     ss += (bf_lo(w.z) * bf_lo(w.z) + bf_hi(w.z) * bf_hi(w.z)) + (bf_lo(w.w) * bf_lo(w.w) + bf_hi(w.w) * bf_hi(w.w)); }
;                 ss = fq_sum(ss);
;                 if (fq == 0) part[(size_t)(row0 + ai * HALF + m * 16) * 16 + u.pn * 4 + wc] = ss; } }
.LBB0_733:
	s_or_b64 exec, exec, s[50:51]
	v_add_u32_e32 v114, 16, v148
	v_ashrrev_i32_e32 v115, 31, v114
	v_lshlrev_b64 v[116:117], 11, v[114:115]
	v_lshl_add_u64 v[116:117], s[94:95], 0, v[116:117]
	v_lshl_add_u64 v[120:121], v[146:147], 1, v[116:117]
	s_nop 0
	s_waitcnt vmcnt(15)
	v_lshlrev_b32_e32 v122, 16, v190
	v_and_b32_e32 v116, 0xffff0000, v190
	v_lshlrev_b32_e32 v123, 16, v191
	v_and_b32_e32 v117, 0xffff0000, v191
	v_lshlrev_b32_e32 v124, 16, v192
	v_and_b32_e32 v118, 0xffff0000, v192
	v_lshlrev_b32_e32 v125, 16, v193
	v_and_b32_e32 v119, 0xffff0000, v193
	v_fmac_f32_e32 v122, 0.5, v110
	v_fmac_f32_e32 v116, 0.5, v111
	v_fmac_f32_e32 v123, 0.5, v112
	v_fmac_f32_e32 v117, 0.5, v113
	v_fmac_f32_e32 v124, 0.5, v106
	v_fmac_f32_e32 v118, 0.5, v107
	v_fmac_f32_e32 v125, 0.5, v108
	v_fmac_f32_e32 v119, 0.5, v109
	v_cvt_pk_bf16_f32 v106, v122, v116
	v_cvt_pk_bf16_f32 v107, v123, v117
	v_cvt_pk_bf16_f32 v108, v124, v118
	v_cvt_pk_bf16_f32 v109, v125, v119
	s_nop 0
	v_lshlrev_b32_e32 v116, 16, v106
	global_store_dwordx4 v[120:121], v[106:109], off
	v_lshlrev_b32_e32 v117, 16, v107
	v_lshlrev_b32_e32 v118, 16, v108
	v_and_b32_e32 v106, 0xffff0000, v106
	v_and_b32_e32 v107, 0xffff0000, v107
	v_and_b32_e32 v108, 0xffff0000, v108
	v_lshlrev_b32_e32 v119, 16, v109
	v_and_b32_e32 v109, 0xffff0000, v109
	v_mul_f32_e32 v106, v106, v106
	v_mul_f32_e32 v107, v107, v107
	v_mul_f32_e32 v108, v108, v108
	v_mul_f32_e32 v109, v109, v109
	v_fmac_f32_e32 v106, v116, v116
	v_fmac_f32_e32 v107, v117, v117
	v_fmac_f32_e32 v108, v118, v118
	v_fmac_f32_e32 v109, v119, v119
	v_add_f32_e32 v106, v106, v107
	v_add_f32_e32 v107, v108, v109
	v_add_f32_e32 v106, v106, v107
	s_waitcnt vmcnt(15)
	v_lshlrev_b32_e32 v107, 16, v194
	v_and_b32_e32 v108, 0xffff0000, v194
	v_lshlrev_b32_e32 v109, 16, v195
	v_and_b32_e32 v110, 0xffff0000, v195
	v_lshlrev_b32_e32 v111, 16, v196
	v_and_b32_e32 v112, 0xffff0000, v196
	v_lshlrev_b32_e32 v116, 16, v197
	v_and_b32_e32 v113, 0xffff0000, v197
	v_fmac_f32_e32 v107, 0.5, v102
	v_fmac_f32_e32 v108, 0.5, v103
	v_fmac_f32_e32 v109, 0.5, v104
	v_fmac_f32_e32 v110, 0.5, v105
	v_fmac_f32_e32 v111, 0.5, v98
	v_fmac_f32_e32 v112, 0.5, v99
	v_cvt_pk_bf16_f32 v98, v107, v108
	v_cvt_pk_bf16_f32 v99, v109, v110
	v_fmac_f32_e32 v116, 0.5, v100
	v_and_b32_e32 v103, 0xffff0000, v98
	v_and_b32_e32 v105, 0xffff0000, v99
	v_fmac_f32_e32 v113, 0.5, v101
	v_cvt_pk_bf16_f32 v100, v111, v112
	v_cvt_pk_bf16_f32 v101, v116, v113
	v_lshlrev_b32_e32 v102, 16, v98
	v_lshlrev_b32_e32 v104, 16, v99
	v_and_b32_e32 v108, 0xffff0000, v100
	v_and_b32_e32 v110, 0xffff0000, v101
	v_mul_f32_e32 v103, v103, v103
	v_mul_f32_e32 v105, v105, v105
	v_lshlrev_b32_e32 v107, 16, v100
	v_lshlrev_b32_e32 v109, 16, v101
	v_mul_f32_e32 v108, v108, v108
	v_mul_f32_e32 v110, v110, v110
	v_fmac_f32_e32 v103, v102, v102
	v_fmac_f32_e32 v105, v104, v104
	v_fmac_f32_e32 v108, v107, v107
	v_fmac_f32_e32 v110, v109, v109
	v_add_f32_e32 v102, v103, v105
	v_add_f32_e32 v103, v108, v110
	v_add_f32_e32 v102, v106, v102
	v_add_f32_e32 v102, v102, v103
	ds_swizzle_b32 v103, v102 offset:swizzle(SWAP,16)
	global_store_dwordx4 v[120:121], v[98:101], off offset:256
	s_waitcnt lgkmcnt(0)
	s_nop 0
	v_add_f32_e32 v98, v102, v103
	v_mov_b32_e32 v99, v98
	s_nop 1
	v_permlane32_swap_b32_e32 v98, v99
	s_and_saveexec_b64 s[50:51], vcc
	s_cbranch_execz .LBB0_735
	v_lshlrev_b64 v[100:101], 6, v[114:115]
	v_lshl_add_u64 v[100:101], s[96:97], 0, v[100:101]
	v_lshl_add_u64 v[100:101], s[48:49], 2, v[100:101]
	s_lshl_b32 s58, s70, 2
	v_lshl_add_u64 v[100:101], v[100:101], 0, s[58:59]
	v_add_f32_e32 v98, v98, v99
	global_store_dword v[100:101], v98, off
.LBB0_735:
	s_or_b64 exec, exec, s[50:51]
	v_add_u32_e32 v98, 32, v148
	v_ashrrev_i32_e32 v99, 31, v98
	v_lshlrev_b64 v[100:101], 11, v[98:99]
	v_lshl_add_u64 v[100:101], s[94:95], 0, v[100:101]
	v_lshl_add_u64 v[104:105], v[146:147], 1, v[100:101]
	s_nop 0
	s_waitcnt vmcnt(15)
	v_lshlrev_b32_e32 v106, 16, v198
	v_and_b32_e32 v100, 0xffff0000, v198
	v_lshlrev_b32_e32 v107, 16, v199
	v_and_b32_e32 v101, 0xffff0000, v199
	v_lshlrev_b32_e32 v108, 16, v200
	v_and_b32_e32 v102, 0xffff0000, v200
	v_lshlrev_b32_e32 v109, 16, v201
	v_and_b32_e32 v103, 0xffff0000, v201
	v_fmac_f32_e32 v106, 0.5, v94
	v_fmac_f32_e32 v100, 0.5, v95
	v_fmac_f32_e32 v107, 0.5, v96
	v_fmac_f32_e32 v101, 0.5, v97
	v_fmac_f32_e32 v108, 0.5, v90
	v_fmac_f32_e32 v102, 0.5, v91
	v_fmac_f32_e32 v109, 0.5, v92
	v_fmac_f32_e32 v103, 0.5, v93
	v_cvt_pk_bf16_f32 v90, v106, v100
	v_cvt_pk_bf16_f32 v91, v107, v101
	v_cvt_pk_bf16_f32 v92, v108, v102
	v_cvt_pk_bf16_f32 v93, v109, v103
	s_nop 0
	v_lshlrev_b32_e32 v100, 16, v90
	global_store_dwordx4 v[104:105], v[90:93], off
	v_lshlrev_b32_e32 v101, 16, v91
	v_lshlrev_b32_e32 v102, 16, v92
	v_and_b32_e32 v90, 0xffff0000, v90
	v_and_b32_e32 v91, 0xffff0000, v91
	v_and_b32_e32 v92, 0xffff0000, v92
	v_lshlrev_b32_e32 v103, 16, v93
	v_and_b32_e32 v93, 0xffff0000, v93
	v_mul_f32_e32 v90, v90, v90
	v_mul_f32_e32 v91, v91, v91
	v_mul_f32_e32 v92, v92, v92
	v_mul_f32_e32 v93, v93, v93
	v_fmac_f32_e32 v90, v100, v100
	v_fmac_f32_e32 v91, v101, v101
	v_fmac_f32_e32 v92, v102, v102
	v_fmac_f32_e32 v93, v103, v103
	v_add_f32_e32 v90, v90, v91
	v_add_f32_e32 v91, v92, v93
	v_add_f32_e32 v90, v90, v91
	s_waitcnt vmcnt(15)
	v_lshlrev_b32_e32 v91, 16, v202
	v_and_b32_e32 v92, 0xffff0000, v202
	v_lshlrev_b32_e32 v93, 16, v203
	v_and_b32_e32 v94, 0xffff0000, v203
	v_lshlrev_b32_e32 v95, 16, v204
	v_and_b32_e32 v96, 0xffff0000, v204
	v_lshlrev_b32_e32 v100, 16, v205
	v_and_b32_e32 v97, 0xffff0000, v205
	v_fmac_f32_e32 v91, 0.5, v86
	v_fmac_f32_e32 v92, 0.5, v87
	v_fmac_f32_e32 v93, 0.5, v88
	v_fmac_f32_e32 v94, 0.5, v89
	v_fmac_f32_e32 v95, 0.5, v82
	v_fmac_f32_e32 v96, 0.5, v83
	v_cvt_pk_bf16_f32 v82, v91, v92
	v_cvt_pk_bf16_f32 v83, v93, v94
	v_fmac_f32_e32 v100, 0.5, v84
	v_and_b32_e32 v87, 0xffff0000, v82
	v_and_b32_e32 v89, 0xffff0000, v83
	v_fmac_f32_e32 v97, 0.5, v85
	v_cvt_pk_bf16_f32 v84, v95, v96
	v_cvt_pk_bf16_f32 v85, v100, v97
	v_lshlrev_b32_e32 v86, 16, v82
	v_lshlrev_b32_e32 v88, 16, v83
	v_and_b32_e32 v92, 0xffff0000, v84
	v_and_b32_e32 v94, 0xffff0000, v85
	v_mul_f32_e32 v87, v87, v87
	v_mul_f32_e32 v89, v89, v89
	v_lshlrev_b32_e32 v91, 16, v84
	v_lshlrev_b32_e32 v93, 16, v85
	v_mul_f32_e32 v92, v92, v92
	v_mul_f32_e32 v94, v94, v94
	v_fmac_f32_e32 v87, v86, v86
	v_fmac_f32_e32 v89, v88, v88
	v_fmac_f32_e32 v92, v91, v91
	v_fmac_f32_e32 v94, v93, v93
	v_add_f32_e32 v86, v87, v89
	v_add_f32_e32 v87, v92, v94
	v_add_f32_e32 v86, v90, v86
	v_add_f32_e32 v86, v86, v87
	ds_swizzle_b32 v87, v86 offset:swizzle(SWAP,16)
	global_store_dwordx4 v[104:105], v[82:85], off offset:256
	s_waitcnt lgkmcnt(0)
	s_nop 0
	v_add_f32_e32 v82, v86, v87
	v_mov_b32_e32 v83, v82
	s_nop 1
	v_permlane32_swap_b32_e32 v82, v83
	s_and_saveexec_b64 s[50:51], vcc
	s_cbranch_execz .LBB0_737
; __device__ __forceinline__ unsigned cvt_pk_bf16(float lo, float hi) { unsigned r; asm volatile("v_cvt_pk_bf16_f32 %0, %1, %2" : "=v"(r) : "v"(lo), "v"(hi)); return r; }
; __device__ __forceinline__ float bf_lo(unsigned w) { return __uint_as_float(w << 16); }
; __device__ __forceinline__ float bf_hi(unsigned w) { return __uint_as_float(w & 0xffff0000u); }
;     __device__ __forceinline__ void operator()(const f32x4 (&acc)[2][2][4][2], const Unit& u, int wr, int wc, int fr, int fq, const float (&rs)[2][4]) const {
;     ...
;             for (int m = 0; m < 4; ++m) { bf16_t* rowp = X + (size_t)(row0 + ai * HALF + m * 16) * DM + col0; float ss = 0.f;
; #pragma unroll
;                 for (int bj = 0; bj < 2; ++bj) { const u32x4 bw = *(const u32x4*)(rowp + bj * HALF); const f32x4 a0 = acc[ai][bj][m][0], a1 = acc[ai][bj][m][1];
;                     u32x4 w; w.x = cvt_pk_bf16(bf_lo(bw.x) + alpha * a0[0], bf_hi(bw.x) + alpha * a0[1]); w.y = cvt_pk_bf16(bf_lo(bw.y) + alpha * a0[2], bf_hi(bw.y) + alpha * a0[3]);
;                     w.z = cvt_pk_bf16(bf_lo(bw.z) + alpha * a1[0], bf_hi(bw.z) + alpha * a1[1]); w.w = cvt_pk_bf16(bf_lo(bw.w) + alpha * a1[2], bf_hi(bw.w) + alpha * a1[3]);
;                     *(u32x4*)(rowp + bj * HALF) = w;
;                     ss += (bf_lo(w.x) * bf_lo(w.x) + bf_hi(w.x) * bf_hi(w.x)) + (bf_lo(w.y) * bf_lo(w.y) + bf_hi(w.y) * bf_hi(w.y));
;                     ss += (bf_lo(w.z) * bf_lo(w.z) + bf_hi(w.z) * bf_hi(w.z)) + (bf_lo(w.w) * bf_lo(w.w) + bf_hi(w.w) * bf_hi(w.w)); }
;                 ss = fq_sum(ss);
;                 if (fq == 0) part[(size_t)(row0 + ai * HALF + m * 16) * 16 + u.pn * 4 + wc] = ss; } }
	v_lshlrev_b64 v[84:85], 6, v[98:99]
	v_lshl_add_u64 v[84:85], s[96:97], 0, v[84:85]
	v_lshl_add_u64 v[84:85], s[48:49], 2, v[84:85]
	s_lshl_b32 s58, s70, 2
	v_lshl_add_u64 v[84:85], v[84:85], 0, s[58:59]
	v_add_f32_e32 v82, v82, v83
	global_store_dword v[84:85], v82, off
.LBB0_737:
	s_or_b64 exec, exec, s[50:51]
	v_add_u32_e32 v82, 48, v148
	v_ashrrev_i32_e32 v83, 31, v82
	v_lshlrev_b64 v[84:85], 11, v[82:83]
	v_lshl_add_u64 v[84:85], s[94:95], 0, v[84:85]
	v_lshl_add_u64 v[84:85], v[146:147], 1, v[84:85]
	s_nop 0
	s_waitcnt vmcnt(15)
	v_lshlrev_b32_e32 v90, 16, v206
	v_and_b32_e32 v86, 0xffff0000, v206
	v_lshlrev_b32_e32 v91, 16, v207
	v_and_b32_e32 v87, 0xffff0000, v207
	v_lshlrev_b32_e32 v92, 16, v208
	v_and_b32_e32 v88, 0xffff0000, v208
	v_lshlrev_b32_e32 v93, 16, v209
	v_and_b32_e32 v89, 0xffff0000, v209
	v_fmac_f32_e32 v90, 0.5, v76
	v_fmac_f32_e32 v86, 0.5, v77
	v_fmac_f32_e32 v91, 0.5, v78
	v_fmac_f32_e32 v87, 0.5, v79
	v_fmac_f32_e32 v92, 0.5, v72
	v_fmac_f32_e32 v88, 0.5, v73
	v_fmac_f32_e32 v93, 0.5, v74
	v_fmac_f32_e32 v89, 0.5, v75
	v_cvt_pk_bf16_f32 v72, v90, v86
	v_cvt_pk_bf16_f32 v73, v91, v87
	v_cvt_pk_bf16_f32 v74, v92, v88
	v_cvt_pk_bf16_f32 v75, v93, v89
	s_nop 0
	v_lshlrev_b32_e32 v86, 16, v72
	global_store_dwordx4 v[84:85], v[72:75], off
	v_lshlrev_b32_e32 v87, 16, v73
	v_lshlrev_b32_e32 v88, 16, v74
	v_and_b32_e32 v72, 0xffff0000, v72
	v_and_b32_e32 v73, 0xffff0000, v73
	v_and_b32_e32 v74, 0xffff0000, v74
	v_lshlrev_b32_e32 v89, 16, v75
	v_and_b32_e32 v75, 0xffff0000, v75
	v_mul_f32_e32 v72, v72, v72
	v_mul_f32_e32 v73, v73, v73
	v_mul_f32_e32 v74, v74, v74
	v_mul_f32_e32 v75, v75, v75
	v_fmac_f32_e32 v72, v86, v86
	v_fmac_f32_e32 v73, v87, v87
	v_fmac_f32_e32 v74, v88, v88
	v_fmac_f32_e32 v75, v89, v89
	v_add_f32_e32 v72, v72, v73
	v_add_f32_e32 v73, v74, v75
	v_add_f32_e32 v72, v72, v73
	s_waitcnt vmcnt(15)
	v_lshlrev_b32_e32 v73, 16, v210
	v_and_b32_e32 v74, 0xffff0000, v210
	v_lshlrev_b32_e32 v75, 16, v211
	v_and_b32_e32 v76, 0xffff0000, v211
	v_lshlrev_b32_e32 v77, 16, v212
	v_and_b32_e32 v78, 0xffff0000, v212
	v_lshlrev_b32_e32 v86, 16, v213
	v_and_b32_e32 v79, 0xffff0000, v213
	v_fmac_f32_e32 v73, 0.5, v68
	v_fmac_f32_e32 v74, 0.5, v69
	v_fmac_f32_e32 v75, 0.5, v70
	v_fmac_f32_e32 v76, 0.5, v71
	v_fmac_f32_e32 v77, 0.5, v64
	v_fmac_f32_e32 v78, 0.5, v65
	v_cvt_pk_bf16_f32 v64, v73, v74
	v_cvt_pk_bf16_f32 v65, v75, v76
	v_fmac_f32_e32 v86, 0.5, v66
	v_and_b32_e32 v69, 0xffff0000, v64
	v_and_b32_e32 v71, 0xffff0000, v65
	v_fmac_f32_e32 v79, 0.5, v67
	v_cvt_pk_bf16_f32 v66, v77, v78
	v_cvt_pk_bf16_f32 v67, v86, v79
	v_lshlrev_b32_e32 v68, 16, v64
	v_lshlrev_b32_e32 v70, 16, v65
	v_and_b32_e32 v74, 0xffff0000, v66
	v_and_b32_e32 v76, 0xffff0000, v67
	v_mul_f32_e32 v69, v69, v69
	v_mul_f32_e32 v71, v71, v71
	v_lshlrev_b32_e32 v73, 16, v66
	v_lshlrev_b32_e32 v75, 16, v67
	v_mul_f32_e32 v74, v74, v74
	v_mul_f32_e32 v76, v76, v76
	v_fmac_f32_e32 v69, v68, v68
	v_fmac_f32_e32 v71, v70, v70
	v_fmac_f32_e32 v74, v73, v73
	v_fmac_f32_e32 v76, v75, v75
	v_add_f32_e32 v68, v69, v71
	v_add_f32_e32 v69, v74, v76
	v_add_f32_e32 v68, v72, v68
	v_add_f32_e32 v68, v68, v69
	ds_swizzle_b32 v69, v68 offset:swizzle(SWAP,16)
	global_store_dwordx4 v[84:85], v[64:67], off offset:256
	s_waitcnt lgkmcnt(0)
	s_nop 0
	v_add_f32_e32 v64, v68, v69
	v_mov_b32_e32 v65, v64
	s_nop 1
	v_permlane32_swap_b32_e32 v64, v65
	s_and_saveexec_b64 s[50:51], vcc
	s_cbranch_execz .LBB0_739
	v_lshlrev_b64 v[66:67], 6, v[82:83]
	v_lshl_add_u64 v[66:67], s[96:97], 0, v[66:67]
	v_lshl_add_u64 v[66:67], s[48:49], 2, v[66:67]
	s_lshl_b32 s58, s70, 2
	v_lshl_add_u64 v[66:67], v[66:67], 0, s[58:59]
	v_add_f32_e32 v64, v64, v65
	global_store_dword v[66:67], v64, off
.LBB0_739:
	s_or_b64 exec, exec, s[50:51]
	v_add_u32_e32 v64, 0x80, v148
	v_ashrrev_i32_e32 v65, 31, v64
	v_lshlrev_b64 v[66:67], 11, v[64:65]
	v_lshl_add_u64 v[66:67], s[94:95], 0, v[66:67]
	v_lshl_add_u64 v[70:71], v[146:147], 1, v[66:67]
	s_nop 0
	s_waitcnt vmcnt(15)
	v_lshlrev_b32_e32 v72, 16, v214
	v_and_b32_e32 v66, 0xffff0000, v214
	v_lshlrev_b32_e32 v73, 16, v215
	v_and_b32_e32 v67, 0xffff0000, v215
	v_lshlrev_b32_e32 v74, 16, v216
	v_and_b32_e32 v68, 0xffff0000, v216
	v_lshlrev_b32_e32 v75, 16, v217
	v_and_b32_e32 v69, 0xffff0000, v217
	v_fmac_f32_e32 v72, 0.5, v60
	v_fmac_f32_e32 v66, 0.5, v61
	v_fmac_f32_e32 v73, 0.5, v62
	v_fmac_f32_e32 v67, 0.5, v63
	v_fmac_f32_e32 v74, 0.5, v56
	v_fmac_f32_e32 v68, 0.5, v57
	v_fmac_f32_e32 v75, 0.5, v58
	v_fmac_f32_e32 v69, 0.5, v59
	v_cvt_pk_bf16_f32 v56, v72, v66
	v_cvt_pk_bf16_f32 v57, v73, v67
	v_cvt_pk_bf16_f32 v58, v74, v68
	v_cvt_pk_bf16_f32 v59, v75, v69
	s_nop 0
	v_lshlrev_b32_e32 v66, 16, v56
	global_store_dwordx4 v[70:71], v[56:59], off
	v_lshlrev_b32_e32 v67, 16, v57
	v_lshlrev_b32_e32 v68, 16, v58
	v_and_b32_e32 v56, 0xffff0000, v56
	v_and_b32_e32 v57, 0xffff0000, v57
	v_and_b32_e32 v58, 0xffff0000, v58
	v_lshlrev_b32_e32 v69, 16, v59
	v_and_b32_e32 v59, 0xffff0000, v59
	v_mul_f32_e32 v56, v56, v56
	v_mul_f32_e32 v57, v57, v57
	v_mul_f32_e32 v58, v58, v58
	v_mul_f32_e32 v59, v59, v59
	v_fmac_f32_e32 v56, v66, v66
	v_fmac_f32_e32 v57, v67, v67
	v_fmac_f32_e32 v58, v68, v68
	v_fmac_f32_e32 v59, v69, v69
	v_add_f32_e32 v56, v56, v57
	v_add_f32_e32 v57, v58, v59
	v_add_f32_e32 v56, v56, v57
	s_waitcnt vmcnt(15)
	v_lshlrev_b32_e32 v57, 16, v218
	v_and_b32_e32 v58, 0xffff0000, v218
	v_lshlrev_b32_e32 v59, 16, v219
	v_and_b32_e32 v60, 0xffff0000, v219
	v_lshlrev_b32_e32 v61, 16, v220
	v_and_b32_e32 v62, 0xffff0000, v220
	v_lshlrev_b32_e32 v66, 16, v221
	v_and_b32_e32 v63, 0xffff0000, v221
	v_fmac_f32_e32 v57, 0.5, v52
	v_fmac_f32_e32 v58, 0.5, v53
	v_fmac_f32_e32 v59, 0.5, v54
	v_fmac_f32_e32 v60, 0.5, v55
	v_fmac_f32_e32 v61, 0.5, v48
	v_fmac_f32_e32 v62, 0.5, v49
	v_cvt_pk_bf16_f32 v48, v57, v58
	v_cvt_pk_bf16_f32 v49, v59, v60
	v_fmac_f32_e32 v66, 0.5, v50
	v_and_b32_e32 v53, 0xffff0000, v48
	v_and_b32_e32 v55, 0xffff0000, v49
	v_fmac_f32_e32 v63, 0.5, v51
	v_cvt_pk_bf16_f32 v50, v61, v62
	v_cvt_pk_bf16_f32 v51, v66, v63
	v_lshlrev_b32_e32 v52, 16, v48
	v_lshlrev_b32_e32 v54, 16, v49
	v_and_b32_e32 v58, 0xffff0000, v50
	v_and_b32_e32 v60, 0xffff0000, v51
	v_mul_f32_e32 v53, v53, v53
	v_mul_f32_e32 v55, v55, v55
	v_lshlrev_b32_e32 v57, 16, v50
	v_lshlrev_b32_e32 v59, 16, v51
	v_mul_f32_e32 v58, v58, v58
	v_mul_f32_e32 v60, v60, v60
	v_fmac_f32_e32 v53, v52, v52
	v_fmac_f32_e32 v55, v54, v54
	v_fmac_f32_e32 v58, v57, v57
	v_fmac_f32_e32 v60, v59, v59
	v_add_f32_e32 v52, v53, v55
	v_add_f32_e32 v53, v58, v60
	v_add_f32_e32 v52, v56, v52
	v_add_f32_e32 v52, v52, v53
	ds_swizzle_b32 v53, v52 offset:swizzle(SWAP,16)
	global_store_dwordx4 v[70:71], v[48:51], off offset:256
	s_waitcnt lgkmcnt(0)
	s_nop 0
	v_add_f32_e32 v48, v52, v53
	v_mov_b32_e32 v49, v48
	s_nop 1
	v_permlane32_swap_b32_e32 v48, v49
	s_and_saveexec_b64 s[50:51], vcc
	s_cbranch_execz .LBB0_741
; __device__ __forceinline__ unsigned cvt_pk_bf16(float lo, float hi) { unsigned r; asm volatile("v_cvt_pk_bf16_f32 %0, %1, %2" : "=v"(r) : "v"(lo), "v"(hi)); return r; }
; __device__ __forceinline__ float bf_lo(unsigned w) { return __uint_as_float(w << 16); }
; __device__ __forceinline__ float bf_hi(unsigned w) { return __uint_as_float(w & 0xffff0000u); }
;     __device__ __forceinline__ void operator()(const f32x4 (&acc)[2][2][4][2], const Unit& u, int wr, int wc, int fr, int fq, const float (&rs)[2][4]) const {
;     ...
;             for (int m = 0; m < 4; ++m) { bf16_t* rowp = X + (size_t)(row0 + ai * HALF + m * 16) * DM + col0; float ss = 0.f;
; #pragma unroll
;                 for (int bj = 0; bj < 2; ++bj) { const u32x4 bw = *(const u32x4*)(rowp + bj * HALF); const f32x4 a0 = acc[ai][bj][m][0], a1 = acc[ai][bj][m][1];
;                     u32x4 w; w.x = cvt_pk_bf16(bf_lo(bw.x) + alpha * a0[0], bf_hi(bw.x) + alpha * a0[1]); w.y = cvt_pk_bf16(bf_lo(bw.y) + alpha * a0[2], bf_hi(bw.y) + alpha * a0[3]);
;                     w.z = cvt_pk_bf16(bf_lo(bw.z) + alpha * a1[0], bf_hi(bw.z) + alpha * a1[1]); w.w = cvt_pk_bf16(bf_lo(bw.w) + alpha * a1[2], bf_hi(bw.w) + alpha * a1[3]);
;                     *(u32x4*)(rowp + bj * HALF) = w;
;                     ss += (bf_lo(w.x) * bf_lo(w.x) + bf_hi(w.x) * bf_hi(w.x)) + (bf_lo(w.y) * bf_lo(w.y) + bf_hi(w.y) * bf_hi(w.y));
;                     ss += (bf_lo(w.z) * bf_lo(w.z) + bf_hi(w.z) * bf_hi(w.z)) + (bf_lo(w.w) * bf_lo(w.w) + bf_hi(w.w) * bf_hi(w.w)); }
;                 ss = fq_sum(ss);
;                 if (fq == 0) part[(size_t)(row0 + ai * HALF + m * 16) * 16 + u.pn * 4 + wc] = ss; } }
	v_lshlrev_b64 v[50:51], 6, v[64:65]
	v_lshl_add_u64 v[50:51], s[96:97], 0, v[50:51]
	v_lshl_add_u64 v[50:51], s[48:49], 2, v[50:51]
	s_lshl_b32 s58, s70, 2
	v_lshl_add_u64 v[50:51], v[50:51], 0, s[58:59]
	v_add_f32_e32 v48, v48, v49
	global_store_dword v[50:51], v48, off
.LBB0_741:
	s_or_b64 exec, exec, s[50:51]
	v_add_u32_e32 v48, 0x90, v148
	v_ashrrev_i32_e32 v49, 31, v48
	v_lshlrev_b64 v[50:51], 11, v[48:49]
	v_lshl_add_u64 v[50:51], s[94:95], 0, v[50:51]
	v_lshl_add_u64 v[54:55], v[146:147], 1, v[50:51]
	s_nop 0
	s_waitcnt vmcnt(15)
	v_lshlrev_b32_e32 v56, 16, v222
	v_and_b32_e32 v50, 0xffff0000, v222
	v_lshlrev_b32_e32 v57, 16, v223
	v_and_b32_e32 v51, 0xffff0000, v223
	v_lshlrev_b32_e32 v58, 16, v224
	v_and_b32_e32 v52, 0xffff0000, v224
	v_lshlrev_b32_e32 v59, 16, v225
	v_and_b32_e32 v53, 0xffff0000, v225
	v_fmac_f32_e32 v56, 0.5, v44
	v_fmac_f32_e32 v50, 0.5, v45
	v_fmac_f32_e32 v57, 0.5, v46
	v_fmac_f32_e32 v51, 0.5, v47
	v_fmac_f32_e32 v58, 0.5, v40
	v_fmac_f32_e32 v52, 0.5, v41
	v_fmac_f32_e32 v59, 0.5, v42
	v_fmac_f32_e32 v53, 0.5, v43
	v_cvt_pk_bf16_f32 v40, v56, v50
	v_cvt_pk_bf16_f32 v41, v57, v51
	v_cvt_pk_bf16_f32 v42, v58, v52
	v_cvt_pk_bf16_f32 v43, v59, v53
	s_nop 0
	v_lshlrev_b32_e32 v50, 16, v40
	global_store_dwordx4 v[54:55], v[40:43], off
	v_lshlrev_b32_e32 v51, 16, v41
	v_lshlrev_b32_e32 v52, 16, v42
	v_and_b32_e32 v40, 0xffff0000, v40
	v_and_b32_e32 v41, 0xffff0000, v41
	v_and_b32_e32 v42, 0xffff0000, v42
	v_lshlrev_b32_e32 v53, 16, v43
	v_and_b32_e32 v43, 0xffff0000, v43
	v_mul_f32_e32 v40, v40, v40
	v_mul_f32_e32 v41, v41, v41
	v_mul_f32_e32 v42, v42, v42
	v_mul_f32_e32 v43, v43, v43
	v_fmac_f32_e32 v40, v50, v50
	v_fmac_f32_e32 v41, v51, v51
	v_fmac_f32_e32 v42, v52, v52
	v_fmac_f32_e32 v43, v53, v53
	v_add_f32_e32 v40, v40, v41
	v_add_f32_e32 v41, v42, v43
	v_add_f32_e32 v40, v40, v41
	s_waitcnt vmcnt(15)
	v_lshlrev_b32_e32 v41, 16, v226
	v_and_b32_e32 v42, 0xffff0000, v226
	v_lshlrev_b32_e32 v43, 16, v227
	v_and_b32_e32 v44, 0xffff0000, v227
	v_lshlrev_b32_e32 v45, 16, v228
	v_and_b32_e32 v46, 0xffff0000, v228
	v_lshlrev_b32_e32 v50, 16, v229
	v_and_b32_e32 v47, 0xffff0000, v229
	v_fmac_f32_e32 v41, 0.5, v36
	v_fmac_f32_e32 v42, 0.5, v37
	v_fmac_f32_e32 v43, 0.5, v38
	v_fmac_f32_e32 v44, 0.5, v39
	v_fmac_f32_e32 v45, 0.5, v32
	v_fmac_f32_e32 v46, 0.5, v33
	v_cvt_pk_bf16_f32 v32, v41, v42
	v_cvt_pk_bf16_f32 v33, v43, v44
	v_fmac_f32_e32 v50, 0.5, v34
	v_and_b32_e32 v37, 0xffff0000, v32
	v_and_b32_e32 v39, 0xffff0000, v33
	v_fmac_f32_e32 v47, 0.5, v35
	v_cvt_pk_bf16_f32 v34, v45, v46
	v_cvt_pk_bf16_f32 v35, v50, v47
	v_lshlrev_b32_e32 v36, 16, v32
	v_lshlrev_b32_e32 v38, 16, v33
	v_and_b32_e32 v42, 0xffff0000, v34
	v_and_b32_e32 v44, 0xffff0000, v35
	v_mul_f32_e32 v37, v37, v37
	v_mul_f32_e32 v39, v39, v39
	v_lshlrev_b32_e32 v41, 16, v34
	v_lshlrev_b32_e32 v43, 16, v35
	v_mul_f32_e32 v42, v42, v42
	v_mul_f32_e32 v44, v44, v44
	v_fmac_f32_e32 v37, v36, v36
	v_fmac_f32_e32 v39, v38, v38
	v_fmac_f32_e32 v42, v41, v41
	v_fmac_f32_e32 v44, v43, v43
	v_add_f32_e32 v36, v37, v39
	v_add_f32_e32 v37, v42, v44
	v_add_f32_e32 v36, v40, v36
	v_add_f32_e32 v36, v36, v37
	ds_swizzle_b32 v37, v36 offset:swizzle(SWAP,16)
	global_store_dwordx4 v[54:55], v[32:35], off offset:256
	s_waitcnt lgkmcnt(0)
	s_nop 0
	v_add_f32_e32 v32, v36, v37
	v_mov_b32_e32 v33, v32
	s_nop 1
	v_permlane32_swap_b32_e32 v32, v33
	s_and_saveexec_b64 s[50:51], vcc
	s_cbranch_execz .LBB0_743
	v_lshlrev_b64 v[34:35], 6, v[48:49]
	v_lshl_add_u64 v[34:35], s[96:97], 0, v[34:35]
	v_lshl_add_u64 v[34:35], s[48:49], 2, v[34:35]
	s_lshl_b32 s58, s70, 2
	v_lshl_add_u64 v[34:35], v[34:35], 0, s[58:59]
	v_add_f32_e32 v32, v32, v33
	global_store_dword v[34:35], v32, off
; __device__ __forceinline__ unsigned cvt_pk_bf16(float lo, float hi) { unsigned r; asm volatile("v_cvt_pk_bf16_f32 %0, %1, %2" : "=v"(r) : "v"(lo), "v"(hi)); return r; }
; __device__ __forceinline__ float bf_lo(unsigned w) { return __uint_as_float(w << 16); }
; __device__ __forceinline__ float bf_hi(unsigned w) { return __uint_as_float(w & 0xffff0000u); }
;     __device__ __forceinline__ void operator()(const f32x4 (&acc)[2][2][4][2], const Unit& u, int wr, int wc, int fr, int fq, const float (&rs)[2][4]) const {
;     ...
;             for (int m = 0; m < 4; ++m) { bf16_t* rowp = X + (size_t)(row0 + ai * HALF + m * 16) * DM + col0; float ss = 0.f;
; #pragma unroll
;                 for (int bj = 0; bj < 2; ++bj) { const u32x4 bw = *(const u32x4*)(rowp + bj * HALF); const f32x4 a0 = acc[ai][bj][m][0], a1 = acc[ai][bj][m][1];
;                     u32x4 w; w.x = cvt_pk_bf16(bf_lo(bw.x) + alpha * a0[0], bf_hi(bw.x) + alpha * a0[1]); w.y = cvt_pk_bf16(bf_lo(bw.y) + alpha * a0[2], bf_hi(bw.y) + alpha * a0[3]);
;                     w.z = cvt_pk_bf16(bf_lo(bw.z) + alpha * a1[0], bf_hi(bw.z) + alpha * a1[1]); w.w = cvt_pk_bf16(bf_lo(bw.w) + alpha * a1[2], bf_hi(bw.w) + alpha * a1[3]);
;                     *(u32x4*)(rowp + bj * HALF) = w;
;                     ss += (bf_lo(w.x) * bf_lo(w.x) + bf_hi(w.x) * bf_hi(w.x)) + (bf_lo(w.y) * bf_lo(w.y) + bf_hi(w.y) * bf_hi(w.y));
;                     ss += (bf_lo(w.z) * bf_lo(w.z) + bf_hi(w.z) * bf_hi(w.z)) + (bf_lo(w.w) * bf_lo(w.w) + bf_hi(w.w) * bf_hi(w.w)); }
;                 ss = fq_sum(ss);
;                 if (fq == 0) part[(size_t)(row0 + ai * HALF + m * 16) * 16 + u.pn * 4 + wc] = ss; } }
.LBB0_743:
	s_or_b64 exec, exec, s[50:51]
	v_add_u32_e32 v32, 0xa0, v148
	v_ashrrev_i32_e32 v33, 31, v32
	v_lshlrev_b64 v[34:35], 11, v[32:33]
	v_lshl_add_u64 v[34:35], s[94:95], 0, v[34:35]
	v_lshl_add_u64 v[38:39], v[146:147], 1, v[34:35]
	s_nop 0
	s_waitcnt vmcnt(15)
	v_lshlrev_b32_e32 v40, 16, v230
	v_and_b32_e32 v34, 0xffff0000, v230
	v_lshlrev_b32_e32 v41, 16, v231
	v_and_b32_e32 v35, 0xffff0000, v231
	v_lshlrev_b32_e32 v42, 16, v232
	v_and_b32_e32 v36, 0xffff0000, v232
	v_lshlrev_b32_e32 v43, 16, v233
	v_and_b32_e32 v37, 0xffff0000, v233
	v_fmac_f32_e32 v40, 0.5, v28
	v_fmac_f32_e32 v34, 0.5, v29
	v_fmac_f32_e32 v41, 0.5, v30
	v_fmac_f32_e32 v35, 0.5, v31
	v_fmac_f32_e32 v42, 0.5, v24
	v_fmac_f32_e32 v36, 0.5, v25
	v_fmac_f32_e32 v43, 0.5, v26
	v_fmac_f32_e32 v37, 0.5, v27
	v_cvt_pk_bf16_f32 v24, v40, v34
	v_cvt_pk_bf16_f32 v25, v41, v35
	v_cvt_pk_bf16_f32 v26, v42, v36
	v_cvt_pk_bf16_f32 v27, v43, v37
	s_nop 0
	v_lshlrev_b32_e32 v34, 16, v24
	global_store_dwordx4 v[38:39], v[24:27], off
	v_lshlrev_b32_e32 v35, 16, v25
	v_lshlrev_b32_e32 v36, 16, v26
	v_and_b32_e32 v24, 0xffff0000, v24
	v_and_b32_e32 v25, 0xffff0000, v25
	v_and_b32_e32 v26, 0xffff0000, v26
	v_lshlrev_b32_e32 v37, 16, v27
	v_and_b32_e32 v27, 0xffff0000, v27
	v_mul_f32_e32 v24, v24, v24
	v_mul_f32_e32 v25, v25, v25
	v_mul_f32_e32 v26, v26, v26
	v_mul_f32_e32 v27, v27, v27
	v_fmac_f32_e32 v24, v34, v34
	v_fmac_f32_e32 v25, v35, v35
	v_fmac_f32_e32 v26, v36, v36
	v_fmac_f32_e32 v27, v37, v37
	v_add_f32_e32 v24, v24, v25
	v_add_f32_e32 v25, v26, v27
	v_add_f32_e32 v24, v24, v25
	s_waitcnt vmcnt(15)
	v_lshlrev_b32_e32 v25, 16, v234
	v_and_b32_e32 v26, 0xffff0000, v234
	v_lshlrev_b32_e32 v27, 16, v235
	v_and_b32_e32 v28, 0xffff0000, v235
	v_lshlrev_b32_e32 v29, 16, v236
	v_and_b32_e32 v30, 0xffff0000, v236
	v_lshlrev_b32_e32 v34, 16, v237
	v_and_b32_e32 v31, 0xffff0000, v237
	v_fmac_f32_e32 v25, 0.5, v20
	v_fmac_f32_e32 v26, 0.5, v21
	v_fmac_f32_e32 v27, 0.5, v22
	v_fmac_f32_e32 v28, 0.5, v23
	v_fmac_f32_e32 v29, 0.5, v16
	v_fmac_f32_e32 v30, 0.5, v17
	v_cvt_pk_bf16_f32 v16, v25, v26
	v_cvt_pk_bf16_f32 v17, v27, v28
	v_fmac_f32_e32 v34, 0.5, v18
	v_and_b32_e32 v21, 0xffff0000, v16
	v_and_b32_e32 v23, 0xffff0000, v17
	v_fmac_f32_e32 v31, 0.5, v19
	v_cvt_pk_bf16_f32 v18, v29, v30
	v_cvt_pk_bf16_f32 v19, v34, v31
	v_lshlrev_b32_e32 v20, 16, v16
	v_lshlrev_b32_e32 v22, 16, v17
	v_and_b32_e32 v26, 0xffff0000, v18
	v_and_b32_e32 v28, 0xffff0000, v19
	v_mul_f32_e32 v21, v21, v21
	v_mul_f32_e32 v23, v23, v23
	v_lshlrev_b32_e32 v25, 16, v18
	v_lshlrev_b32_e32 v27, 16, v19
	v_mul_f32_e32 v26, v26, v26
	v_mul_f32_e32 v28, v28, v28
	v_fmac_f32_e32 v21, v20, v20
	v_fmac_f32_e32 v23, v22, v22
	v_fmac_f32_e32 v26, v25, v25
	v_fmac_f32_e32 v28, v27, v27
	v_add_f32_e32 v20, v21, v23
	v_add_f32_e32 v21, v26, v28
	v_add_f32_e32 v20, v24, v20
	v_add_f32_e32 v20, v20, v21
	ds_swizzle_b32 v21, v20 offset:swizzle(SWAP,16)
	global_store_dwordx4 v[38:39], v[16:19], off offset:256
	s_waitcnt lgkmcnt(0)
	s_nop 0
	v_add_f32_e32 v16, v20, v21
	v_mov_b32_e32 v17, v16
	s_nop 1
	v_permlane32_swap_b32_e32 v16, v17
	s_and_saveexec_b64 s[50:51], vcc
	s_cbranch_execz .LBB0_745
	v_lshlrev_b64 v[18:19], 6, v[32:33]
	v_lshl_add_u64 v[18:19], s[96:97], 0, v[18:19]
	v_lshl_add_u64 v[18:19], s[48:49], 2, v[18:19]
	s_lshl_b32 s58, s70, 2
	v_lshl_add_u64 v[18:19], v[18:19], 0, s[58:59]
	v_add_f32_e32 v16, v16, v17
	global_store_dword v[18:19], v16, off
.LBB0_745:
	s_or_b64 exec, exec, s[50:51]
	v_add_u32_e32 v16, 0xb0, v148
	v_ashrrev_i32_e32 v17, 31, v16
	v_lshlrev_b64 v[18:19], 11, v[16:17]
	v_lshl_add_u64 v[18:19], s[94:95], 0, v[18:19]
	v_lshl_add_u64 v[22:23], v[146:147], 1, v[18:19]
	s_nop 0
	s_waitcnt vmcnt(15)
	v_lshlrev_b32_e32 v24, 16, v238
	v_and_b32_e32 v18, 0xffff0000, v238
	v_lshlrev_b32_e32 v25, 16, v239
	v_and_b32_e32 v19, 0xffff0000, v239
	v_lshlrev_b32_e32 v26, 16, v240
	v_and_b32_e32 v20, 0xffff0000, v240
	v_lshlrev_b32_e32 v27, 16, v241
	v_and_b32_e32 v21, 0xffff0000, v241
	v_fmac_f32_e32 v24, 0.5, v12
	v_fmac_f32_e32 v18, 0.5, v13
	v_fmac_f32_e32 v25, 0.5, v14
	v_fmac_f32_e32 v19, 0.5, v15
	v_fmac_f32_e32 v26, 0.5, v8
	v_fmac_f32_e32 v20, 0.5, v9
	v_fmac_f32_e32 v27, 0.5, v10
	v_fmac_f32_e32 v21, 0.5, v11
	v_cvt_pk_bf16_f32 v8, v24, v18
	v_cvt_pk_bf16_f32 v9, v25, v19
	v_cvt_pk_bf16_f32 v10, v26, v20
	v_cvt_pk_bf16_f32 v11, v27, v21
	s_nop 0
	v_lshlrev_b32_e32 v18, 16, v8
	global_store_dwordx4 v[22:23], v[8:11], off
	v_lshlrev_b32_e32 v19, 16, v9
	v_lshlrev_b32_e32 v20, 16, v10
	v_and_b32_e32 v8, 0xffff0000, v8
	v_and_b32_e32 v9, 0xffff0000, v9
	v_and_b32_e32 v10, 0xffff0000, v10
	v_lshlrev_b32_e32 v21, 16, v11
	v_and_b32_e32 v11, 0xffff0000, v11
	v_mul_f32_e32 v8, v8, v8
	v_mul_f32_e32 v9, v9, v9
	v_mul_f32_e32 v10, v10, v10
	v_mul_f32_e32 v11, v11, v11
	v_fmac_f32_e32 v8, v18, v18
	v_fmac_f32_e32 v9, v19, v19
	v_fmac_f32_e32 v10, v20, v20
	v_fmac_f32_e32 v11, v21, v21
	v_add_f32_e32 v8, v8, v9
	v_add_f32_e32 v9, v10, v11
	v_add_f32_e32 v8, v8, v9
	s_waitcnt vmcnt(15)
	v_lshlrev_b32_e32 v9, 16, v242
	v_and_b32_e32 v10, 0xffff0000, v242
	v_lshlrev_b32_e32 v11, 16, v243
	v_and_b32_e32 v12, 0xffff0000, v243
	v_lshlrev_b32_e32 v13, 16, v244
	v_and_b32_e32 v14, 0xffff0000, v244
	v_lshlrev_b32_e32 v18, 16, v245
	v_and_b32_e32 v15, 0xffff0000, v245
	v_fmac_f32_e32 v9, 0.5, v4
	v_fmac_f32_e32 v10, 0.5, v5
	v_fmac_f32_e32 v11, 0.5, v6
	v_fmac_f32_e32 v12, 0.5, v7
	v_fmac_f32_e32 v13, 0.5, v0
	v_fmac_f32_e32 v14, 0.5, v1
	v_cvt_pk_bf16_f32 v0, v9, v10
	v_cvt_pk_bf16_f32 v1, v11, v12
	v_fmac_f32_e32 v18, 0.5, v2
	v_and_b32_e32 v5, 0xffff0000, v0
	v_and_b32_e32 v7, 0xffff0000, v1
	v_fmac_f32_e32 v15, 0.5, v3
	v_cvt_pk_bf16_f32 v2, v13, v14
	v_cvt_pk_bf16_f32 v3, v18, v15
	v_lshlrev_b32_e32 v4, 16, v0
	v_lshlrev_b32_e32 v6, 16, v1
	v_and_b32_e32 v10, 0xffff0000, v2
	v_and_b32_e32 v12, 0xffff0000, v3
	v_mul_f32_e32 v5, v5, v5
	v_mul_f32_e32 v7, v7, v7
	v_lshlrev_b32_e32 v9, 16, v2
	v_lshlrev_b32_e32 v11, 16, v3
	v_mul_f32_e32 v10, v10, v10
	v_mul_f32_e32 v12, v12, v12
	v_fmac_f32_e32 v5, v4, v4
	v_fmac_f32_e32 v7, v6, v6
	v_fmac_f32_e32 v10, v9, v9
	v_fmac_f32_e32 v12, v11, v11
	v_add_f32_e32 v4, v5, v7
	v_add_f32_e32 v5, v10, v12
	v_add_f32_e32 v4, v8, v4
	v_add_f32_e32 v4, v4, v5
	ds_swizzle_b32 v5, v4 offset:swizzle(SWAP,16)
	global_store_dwordx4 v[22:23], v[0:3], off offset:256
	s_waitcnt lgkmcnt(0)
	s_nop 0
	v_add_f32_e32 v0, v4, v5
	v_mov_b32_e32 v1, v0
	s_nop 1
	v_permlane32_swap_b32_e32 v0, v1
	s_and_saveexec_b64 s[50:51], vcc
	s_cbranch_execz .LBB0_747
	v_lshlrev_b64 v[2:3], 6, v[16:17]
	v_lshl_add_u64 v[2:3], s[96:97], 0, v[2:3]
	v_lshl_add_u64 v[2:3], s[48:49], 2, v[2:3]
	s_lshl_b32 s58, s70, 2
	v_lshl_add_u64 v[2:3], v[2:3], 0, s[58:59]
	v_add_f32_e32 v0, v0, v1
	global_store_dword v[2:3], v0, off

; __device__ __forceinline__ unsigned cvt_pk_bf16(float lo, float hi) { unsigned r; asm volatile("v_cvt_pk_bf16_f32 %0, %1, %2" : "=v"(r) : "v"(lo), "v"(hi)); return r; }
; __device__ __forceinline__ float bf_lo(unsigned w) { return __uint_as_float(w << 16); }
; __device__ __forceinline__ float bf_hi(unsigned w) { return __uint_as_float(w & 0xffff0000u); }
;     __device__ __forceinline__ void operator()(const f32x4 (&acc)[2][2][4][2], const Unit& u, int wr, int wc, int fr, int fq, const float (&rs)[2][4]) const {
;     ...
;             for (int m = 0; m < 4; ++m) { bf16_t* rowp = X + (size_t)(row0 + ai * HALF + m * 16) * DM + col0; float ss = 0.f;
; #pragma unroll
;                 for (int bj = 0; bj < 2; ++bj) { const u32x4 bw = *(const u32x4*)(rowp + bj * HALF); const f32x4 a0 = acc[ai][bj][m][0], a1 = acc[ai][bj][m][1];
;                     u32x4 w; w.x = cvt_pk_bf16(bf_lo(bw.x) + alpha * a0[0], bf_hi(bw.x) + alpha * a0[1]); w.y = cvt_pk_bf16(bf_lo(bw.y) + alpha * a0[2], bf_hi(bw.y) + alpha * a0[3]);
;                     w.z = cvt_pk_bf16(bf_lo(bw.z) + alpha * a1[0], bf_hi(bw.z) + alpha * a1[1]); w.w = cvt_pk_bf16(bf_lo(bw.w) + alpha * a1[2], bf_hi(bw.w) + alpha * a1[3]);
;                     *(u32x4*)(rowp + bj * HALF) = w;
;                     ss += (bf_lo(w.x) * bf_lo(w.x) + bf_hi(w.x) * bf_hi(w.x)) + (bf_lo(w.y) * bf_lo(w.y) + bf_hi(w.y) * bf_hi(w.y));
;                     ss += (bf_lo(w.z) * bf_lo(w.z) + bf_hi(w.z) * bf_hi(w.z)) + (bf_lo(w.w) * bf_lo(w.w) + bf_hi(w.w) * bf_hi(w.w)); }
;                 ss = fq_sum(ss);
;                 if (fq == 0) part[(size_t)(row0 + ai * HALF + m * 16) * 16 + u.pn * 4 + wc] = ss; } }
.LBB0_1434:
	s_lshl_b32 s0, s58, 8
	v_mov_b32_e32 v130, v151
	v_mov_b32_e32 v134, v150
	s_add_i32 s0, s0, s40
	s_lshl_b32 s44, s54, 2
	v_add_u32_e32 v148, s0, v130
	s_lshl_b32 s0, s54, 8
	s_or_b32 s0, s0, s41
	v_ashrrev_i32_e32 v149, 31, v148
	v_lshl_add_u32 v146, v134, 3, s0
	v_lshlrev_b64 v[130:131], 11, v[148:149]
	v_ashrrev_i32_e32 v147, 31, v146
	v_lshl_add_u64 v[130:131], s[94:95], 0, v[130:131]
	v_lshl_add_u64 v[130:131], v[146:147], 1, v[130:131]
	global_load_dwordx4 v[182:185], v[130:131], off
	global_load_dwordx4 v[186:189], v[130:131], off offset:256
	v_add_u32_e32 v246, 16, v148
	v_ashrrev_i32_e32 v247, 31, v246
	v_lshlrev_b64 v[246:247], 11, v[246:247]
	v_lshl_add_u64 v[246:247], s[94:95], 0, v[246:247]
	v_lshl_add_u64 v[246:247], v[146:147], 1, v[246:247]
	global_load_dwordx4 v[190:193], v[246:247], off
	global_load_dwordx4 v[194:197], v[246:247], off offset:256
	v_add_u32_e32 v248, 32, v148
	v_ashrrev_i32_e32 v249, 31, v248
	v_lshlrev_b64 v[248:249], 11, v[248:249]
	v_lshl_add_u64 v[248:249], s[94:95], 0, v[248:249]
	v_lshl_add_u64 v[248:249], v[146:147], 1, v[248:249]
	global_load_dwordx4 v[198:201], v[248:249], off
	global_load_dwordx4 v[202:205], v[248:249], off offset:256
	v_add_u32_e32 v246, 48, v148
	v_ashrrev_i32_e32 v247, 31, v246
	v_lshlrev_b64 v[246:247], 11, v[246:247]
	v_lshl_add_u64 v[246:247], s[94:95], 0, v[246:247]
	v_lshl_add_u64 v[246:247], v[146:147], 1, v[246:247]
	global_load_dwordx4 v[206:209], v[246:247], off
	global_load_dwordx4 v[210:213], v[246:247], off offset:256
	v_add_u32_e32 v248, 0x80, v148
	v_ashrrev_i32_e32 v249, 31, v248
	v_lshlrev_b64 v[248:249], 11, v[248:249]
	v_lshl_add_u64 v[248:249], s[94:95], 0, v[248:249]
	v_lshl_add_u64 v[248:249], v[146:147], 1, v[248:249]
	global_load_dwordx4 v[214:217], v[248:249], off
	global_load_dwordx4 v[218:221], v[248:249], off offset:256
	v_add_u32_e32 v246, 0x90, v148
	v_ashrrev_i32_e32 v247, 31, v246
	v_lshlrev_b64 v[246:247], 11, v[246:247]
	v_lshl_add_u64 v[246:247], s[94:95], 0, v[246:247]
	v_lshl_add_u64 v[246:247], v[146:147], 1, v[246:247]
	global_load_dwordx4 v[222:225], v[246:247], off
	global_load_dwordx4 v[226:229], v[246:247], off offset:256
	v_add_u32_e32 v248, 0xa0, v148
	v_ashrrev_i32_e32 v249, 31, v248
	v_lshlrev_b64 v[248:249], 11, v[248:249]
	v_lshl_add_u64 v[248:249], s[94:95], 0, v[248:249]
	v_lshl_add_u64 v[248:249], v[146:147], 1, v[248:249]
	global_load_dwordx4 v[230:233], v[248:249], off
	global_load_dwordx4 v[234:237], v[248:249], off offset:256
	v_add_u32_e32 v246, 0xb0, v148
	v_ashrrev_i32_e32 v247, 31, v246
	v_lshlrev_b64 v[246:247], 11, v[246:247]
	v_lshl_add_u64 v[246:247], s[94:95], 0, v[246:247]
	v_lshl_add_u64 v[246:247], v[146:147], 1, v[246:247]
	global_load_dwordx4 v[238:241], v[246:247], off
	global_load_dwordx4 v[242:245], v[246:247], off offset:256
	s_ashr_i32 s45, s44, 31
	v_cmp_eq_u32_e32 vcc, 0, v134
	s_waitcnt vmcnt(15)
	v_lshlrev_b32_e32 v135, 16, v182
	v_and_b32_e32 v154, 0xffff0000, v182
	v_lshlrev_b32_e32 v158, 16, v183
	v_and_b32_e32 v155, 0xffff0000, v183
	v_lshlrev_b32_e32 v160, 16, v185
	v_and_b32_e32 v157, 0xffff0000, v185
	v_lshlrev_b32_e32 v159, 16, v184
	v_and_b32_e32 v156, 0xffff0000, v184
	v_add_f32_e32 v126, v126, v135
	v_add_f32_e32 v127, v127, v154
	v_add_f32_e32 v128, v128, v158
	v_add_f32_e32 v129, v129, v155
	v_add_f32_e32 v125, v125, v157
	v_add_f32_e32 v135, v122, v159
	v_add_f32_e32 v154, v123, v156
	v_add_f32_e32 v155, v124, v160
	v_cvt_pk_bf16_f32 v122, v126, v127
	v_cvt_pk_bf16_f32 v123, v128, v129
	v_cvt_pk_bf16_f32 v124, v135, v154
	v_cvt_pk_bf16_f32 v125, v155, v125
	s_nop 0
	v_lshlrev_b32_e32 v135, 16, v122
	global_store_dwordx4 v[130:131], v[122:125], off
	v_lshlrev_b32_e32 v154, 16, v123
	v_lshlrev_b32_e32 v155, 16, v124
	v_and_b32_e32 v122, 0xffff0000, v122
	v_and_b32_e32 v123, 0xffff0000, v123
	v_and_b32_e32 v124, 0xffff0000, v124
	v_lshlrev_b32_e32 v156, 16, v125
	v_and_b32_e32 v125, 0xffff0000, v125
	v_mul_f32_e32 v122, v122, v122
	v_mul_f32_e32 v123, v123, v123
	v_mul_f32_e32 v124, v124, v124
	v_mul_f32_e32 v125, v125, v125
	v_fmac_f32_e32 v122, v135, v135
	v_fmac_f32_e32 v123, v154, v154
	v_fmac_f32_e32 v124, v155, v155
	v_fmac_f32_e32 v125, v156, v156
	v_add_f32_e32 v122, v122, v123
	v_add_f32_e32 v123, v124, v125
	v_add_f32_e32 v122, v122, v123
	s_waitcnt vmcnt(15)
	v_lshlrev_b32_e32 v123, 16, v186
	v_and_b32_e32 v124, 0xffff0000, v186
	v_and_b32_e32 v126, 0xffff0000, v187
	v_lshlrev_b32_e32 v125, 16, v187
	v_lshlrev_b32_e32 v127, 16, v188
	v_and_b32_e32 v128, 0xffff0000, v188
	v_lshlrev_b32_e32 v135, 16, v189
	v_and_b32_e32 v129, 0xffff0000, v189
	v_add_f32_e32 v119, v119, v124
	v_add_f32_e32 v121, v121, v126
	v_add_f32_e32 v118, v118, v123
	v_add_f32_e32 v120, v120, v125
	v_add_f32_e32 v123, v114, v127
	v_add_f32_e32 v124, v115, v128
	v_add_f32_e32 v117, v117, v129
	v_cvt_pk_bf16_f32 v114, v118, v119
	v_cvt_pk_bf16_f32 v115, v120, v121
	v_add_f32_e32 v125, v116, v135
	v_and_b32_e32 v119, 0xffff0000, v114
	v_and_b32_e32 v121, 0xffff0000, v115
	v_cvt_pk_bf16_f32 v116, v123, v124
	v_cvt_pk_bf16_f32 v117, v125, v117
	v_lshlrev_b32_e32 v118, 16, v114
	v_lshlrev_b32_e32 v120, 16, v115
	v_and_b32_e32 v124, 0xffff0000, v116
	v_and_b32_e32 v126, 0xffff0000, v117
	v_mul_f32_e32 v119, v119, v119
	v_mul_f32_e32 v121, v121, v121
	v_lshlrev_b32_e32 v123, 16, v116
	v_lshlrev_b32_e32 v125, 16, v117
	v_mul_f32_e32 v124, v124, v124
	v_mul_f32_e32 v126, v126, v126
	v_fmac_f32_e32 v119, v118, v118
	v_fmac_f32_e32 v121, v120, v120
	v_fmac_f32_e32 v124, v123, v123
	v_fmac_f32_e32 v126, v125, v125
	v_add_f32_e32 v118, v119, v121
	v_add_f32_e32 v119, v124, v126
	v_add_f32_e32 v118, v122, v118
	v_add_f32_e32 v118, v118, v119
	ds_swizzle_b32 v119, v118 offset:swizzle(SWAP,16)
	global_store_dwordx4 v[130:131], v[114:117], off offset:256
	s_waitcnt lgkmcnt(0)
	s_nop 0
	v_add_f32_e32 v114, v118, v119
	v_mov_b32_e32 v115, v114
	s_nop 1
	v_permlane32_swap_b32_e32 v114, v115
	s_and_saveexec_b64 s[54:55], vcc
	s_cbranch_execz .LBB0_1436
	v_lshlrev_b64 v[116:117], 6, v[148:149]
	v_lshl_add_u64 v[116:117], s[96:97], 0, v[116:117]
	v_lshl_add_u64 v[116:117], s[44:45], 2, v[116:117]
	s_lshl_b32 s58, s31, 2
	v_lshl_add_u64 v[116:117], v[116:117], 0, s[58:59]
	v_add_f32_e32 v114, v114, v115
	global_store_dword v[116:117], v114, off
; __device__ __forceinline__ unsigned cvt_pk_bf16(float lo, float hi) { unsigned r; asm volatile("v_cvt_pk_bf16_f32 %0, %1, %2" : "=v"(r) : "v"(lo), "v"(hi)); return r; }
; __device__ __forceinline__ float bf_lo(unsigned w) { return __uint_as_float(w << 16); }
; __device__ __forceinline__ float bf_hi(unsigned w) { return __uint_as_float(w & 0xffff0000u); }
;     __device__ __forceinline__ void operator()(const f32x4 (&acc)[2][2][4][2], const Unit& u, int wr, int wc, int fr, int fq, const float (&rs)[2][4]) const {
;     ...
;             for (int m = 0; m < 4; ++m) { bf16_t* rowp = X + (size_t)(row0 + ai * HALF + m * 16) * DM + col0; float ss = 0.f;
; #pragma unroll
;                 for (int bj = 0; bj < 2; ++bj) { const u32x4 bw = *(const u32x4*)(rowp + bj * HALF); const f32x4 a0 = acc[ai][bj][m][0], a1 = acc[ai][bj][m][1];
;                     u32x4 w; w.x = cvt_pk_bf16(bf_lo(bw.x) + alpha * a0[0], bf_hi(bw.x) + alpha * a0[1]); w.y = cvt_pk_bf16(bf_lo(bw.y) + alpha * a0[2], bf_hi(bw.y) + alpha * a0[3]);
;                     w.z = cvt_pk_bf16(bf_lo(bw.z) + alpha * a1[0], bf_hi(bw.z) + alpha * a1[1]); w.w = cvt_pk_bf16(bf_lo(bw.w) + alpha * a1[2], bf_hi(bw.w) + alpha * a1[3]);
;                     *(u32x4*)(rowp + bj * HALF) = w;
;                     ss += (bf_lo(w.x) * bf_lo(w.x) + bf_hi(w.x) * bf_hi(w.x)) + (bf_lo(w.y) * bf_lo(w.y) + bf_hi(w.y) * bf_hi(w.y));
;                     ss += (bf_lo(w.z) * bf_lo(w.z) + bf_hi(w.z) * bf_hi(w.z)) + (bf_lo(w.w) * bf_lo(w.w) + bf_hi(w.w) * bf_hi(w.w)); }
;                 ss = fq_sum(ss);
;                 if (fq == 0) part[(size_t)(row0 + ai * HALF + m * 16) * 16 + u.pn * 4 + wc] = ss; } }
.LBB0_1436:
	s_or_b64 exec, exec, s[54:55]
	v_add_u32_e32 v114, 16, v148
	v_ashrrev_i32_e32 v115, 31, v114
	v_lshlrev_b64 v[116:117], 11, v[114:115]
	v_lshl_add_u64 v[116:117], s[94:95], 0, v[116:117]
	v_lshl_add_u64 v[120:121], v[146:147], 1, v[116:117]
	s_nop 0
	s_waitcnt vmcnt(15)
	v_lshlrev_b32_e32 v122, 16, v190
	v_and_b32_e32 v116, 0xffff0000, v190
	v_lshlrev_b32_e32 v123, 16, v191
	v_and_b32_e32 v117, 0xffff0000, v191
	v_lshlrev_b32_e32 v125, 16, v193
	v_and_b32_e32 v119, 0xffff0000, v193
	v_lshlrev_b32_e32 v124, 16, v192
	v_and_b32_e32 v118, 0xffff0000, v192
	v_add_f32_e32 v110, v110, v122
	v_add_f32_e32 v111, v111, v116
	v_add_f32_e32 v112, v112, v123
	v_add_f32_e32 v113, v113, v117
	v_add_f32_e32 v109, v109, v119
	v_add_f32_e32 v116, v106, v124
	v_add_f32_e32 v117, v107, v118
	v_add_f32_e32 v118, v108, v125
	v_cvt_pk_bf16_f32 v106, v110, v111
	v_cvt_pk_bf16_f32 v107, v112, v113
	v_cvt_pk_bf16_f32 v108, v116, v117
	v_cvt_pk_bf16_f32 v109, v118, v109
	s_nop 0
	v_lshlrev_b32_e32 v116, 16, v106
	global_store_dwordx4 v[120:121], v[106:109], off
	v_lshlrev_b32_e32 v117, 16, v107
	v_lshlrev_b32_e32 v118, 16, v108
	v_and_b32_e32 v106, 0xffff0000, v106
	v_and_b32_e32 v107, 0xffff0000, v107
	v_and_b32_e32 v108, 0xffff0000, v108
	v_lshlrev_b32_e32 v119, 16, v109
	v_and_b32_e32 v109, 0xffff0000, v109
	v_mul_f32_e32 v106, v106, v106
	v_mul_f32_e32 v107, v107, v107
	v_mul_f32_e32 v108, v108, v108
	v_mul_f32_e32 v109, v109, v109
	v_fmac_f32_e32 v106, v116, v116
	v_fmac_f32_e32 v107, v117, v117
	v_fmac_f32_e32 v108, v118, v118
	v_fmac_f32_e32 v109, v119, v119
	v_add_f32_e32 v106, v106, v107
	v_add_f32_e32 v107, v108, v109
	v_add_f32_e32 v106, v106, v107
	s_waitcnt vmcnt(15)
	v_lshlrev_b32_e32 v107, 16, v194
	v_and_b32_e32 v108, 0xffff0000, v194
	v_and_b32_e32 v110, 0xffff0000, v195
	v_lshlrev_b32_e32 v109, 16, v195
	v_lshlrev_b32_e32 v111, 16, v196
	v_and_b32_e32 v112, 0xffff0000, v196
	v_lshlrev_b32_e32 v116, 16, v197
	v_and_b32_e32 v113, 0xffff0000, v197
	v_add_f32_e32 v103, v103, v108
	v_add_f32_e32 v105, v105, v110
	v_add_f32_e32 v102, v102, v107
	v_add_f32_e32 v104, v104, v109
	v_add_f32_e32 v107, v98, v111
	v_add_f32_e32 v108, v99, v112
	v_add_f32_e32 v101, v101, v113
	v_cvt_pk_bf16_f32 v98, v102, v103
	v_cvt_pk_bf16_f32 v99, v104, v105
	v_add_f32_e32 v109, v100, v116
	v_and_b32_e32 v103, 0xffff0000, v98
	v_and_b32_e32 v105, 0xffff0000, v99
	v_cvt_pk_bf16_f32 v100, v107, v108
	v_cvt_pk_bf16_f32 v101, v109, v101
	v_lshlrev_b32_e32 v102, 16, v98
	v_lshlrev_b32_e32 v104, 16, v99
	v_and_b32_e32 v108, 0xffff0000, v100
	v_and_b32_e32 v110, 0xffff0000, v101
	v_mul_f32_e32 v103, v103, v103
	v_mul_f32_e32 v105, v105, v105
	v_lshlrev_b32_e32 v107, 16, v100
	v_lshlrev_b32_e32 v109, 16, v101
	v_mul_f32_e32 v108, v108, v108
	v_mul_f32_e32 v110, v110, v110
	v_fmac_f32_e32 v103, v102, v102
	v_fmac_f32_e32 v105, v104, v104
	v_fmac_f32_e32 v108, v107, v107
	v_fmac_f32_e32 v110, v109, v109
	v_add_f32_e32 v102, v103, v105
	v_add_f32_e32 v103, v108, v110
	v_add_f32_e32 v102, v106, v102
	v_add_f32_e32 v102, v102, v103
	ds_swizzle_b32 v103, v102 offset:swizzle(SWAP,16)
	global_store_dwordx4 v[120:121], v[98:101], off offset:256
	s_waitcnt lgkmcnt(0)
	s_nop 0
	v_add_f32_e32 v98, v102, v103
	v_mov_b32_e32 v99, v98
	s_nop 1
	v_permlane32_swap_b32_e32 v98, v99
	s_and_saveexec_b64 s[54:55], vcc
	s_cbranch_execz .LBB0_1438
	v_lshlrev_b64 v[100:101], 6, v[114:115]
	v_lshl_add_u64 v[100:101], s[96:97], 0, v[100:101]
	v_lshl_add_u64 v[100:101], s[44:45], 2, v[100:101]
	s_lshl_b32 s58, s31, 2
	v_lshl_add_u64 v[100:101], v[100:101], 0, s[58:59]
	v_add_f32_e32 v98, v98, v99
	global_store_dword v[100:101], v98, off
.LBB0_1438:
	s_or_b64 exec, exec, s[54:55]
	v_add_u32_e32 v98, 32, v148
	v_ashrrev_i32_e32 v99, 31, v98
	v_lshlrev_b64 v[100:101], 11, v[98:99]
	v_lshl_add_u64 v[100:101], s[94:95], 0, v[100:101]
	v_lshl_add_u64 v[104:105], v[146:147], 1, v[100:101]
	s_nop 0
	s_waitcnt vmcnt(15)
	v_lshlrev_b32_e32 v106, 16, v198
	v_and_b32_e32 v100, 0xffff0000, v198
	v_lshlrev_b32_e32 v107, 16, v199
	v_and_b32_e32 v101, 0xffff0000, v199
	v_lshlrev_b32_e32 v109, 16, v201
	v_and_b32_e32 v103, 0xffff0000, v201
	v_lshlrev_b32_e32 v108, 16, v200
	v_and_b32_e32 v102, 0xffff0000, v200
	v_add_f32_e32 v94, v94, v106
	v_add_f32_e32 v95, v95, v100
	v_add_f32_e32 v96, v96, v107
	v_add_f32_e32 v97, v97, v101
	v_add_f32_e32 v93, v93, v103
	v_add_f32_e32 v100, v90, v108
	v_add_f32_e32 v101, v91, v102
	v_add_f32_e32 v102, v92, v109
	v_cvt_pk_bf16_f32 v90, v94, v95
	v_cvt_pk_bf16_f32 v91, v96, v97
	v_cvt_pk_bf16_f32 v92, v100, v101
	v_cvt_pk_bf16_f32 v93, v102, v93
	s_nop 0
	v_lshlrev_b32_e32 v100, 16, v90
	global_store_dwordx4 v[104:105], v[90:93], off
	v_lshlrev_b32_e32 v101, 16, v91
	v_lshlrev_b32_e32 v102, 16, v92
	v_and_b32_e32 v90, 0xffff0000, v90
	v_and_b32_e32 v91, 0xffff0000, v91
	v_and_b32_e32 v92, 0xffff0000, v92
	v_lshlrev_b32_e32 v103, 16, v93
	v_and_b32_e32 v93, 0xffff0000, v93
	v_mul_f32_e32 v90, v90, v90
	v_mul_f32_e32 v91, v91, v91
	v_mul_f32_e32 v92, v92, v92
	v_mul_f32_e32 v93, v93, v93
	v_fmac_f32_e32 v90, v100, v100
	v_fmac_f32_e32 v91, v101, v101
	v_fmac_f32_e32 v92, v102, v102
	v_fmac_f32_e32 v93, v103, v103
	v_add_f32_e32 v90, v90, v91
	v_add_f32_e32 v91, v92, v93
	v_add_f32_e32 v90, v90, v91
	s_waitcnt vmcnt(15)
	v_lshlrev_b32_e32 v91, 16, v202
	v_and_b32_e32 v92, 0xffff0000, v202
	v_and_b32_e32 v94, 0xffff0000, v203
	v_lshlrev_b32_e32 v93, 16, v203
	v_lshlrev_b32_e32 v95, 16, v204
	v_and_b32_e32 v96, 0xffff0000, v204
	v_lshlrev_b32_e32 v100, 16, v205
	v_and_b32_e32 v97, 0xffff0000, v205
	v_add_f32_e32 v87, v87, v92
	v_add_f32_e32 v89, v89, v94
	v_add_f32_e32 v86, v86, v91
	v_add_f32_e32 v88, v88, v93
	v_add_f32_e32 v91, v82, v95
	v_add_f32_e32 v92, v83, v96
	v_add_f32_e32 v85, v85, v97
	v_cvt_pk_bf16_f32 v82, v86, v87
	v_cvt_pk_bf16_f32 v83, v88, v89
	v_add_f32_e32 v93, v84, v100
	v_and_b32_e32 v87, 0xffff0000, v82
	v_and_b32_e32 v89, 0xffff0000, v83
	v_cvt_pk_bf16_f32 v84, v91, v92
	v_cvt_pk_bf16_f32 v85, v93, v85
	v_lshlrev_b32_e32 v86, 16, v82
	v_lshlrev_b32_e32 v88, 16, v83
	v_and_b32_e32 v92, 0xffff0000, v84
	v_and_b32_e32 v94, 0xffff0000, v85
	v_mul_f32_e32 v87, v87, v87
	v_mul_f32_e32 v89, v89, v89
	v_lshlrev_b32_e32 v91, 16, v84
	v_lshlrev_b32_e32 v93, 16, v85
	v_mul_f32_e32 v92, v92, v92
	v_mul_f32_e32 v94, v94, v94
	v_fmac_f32_e32 v87, v86, v86
	v_fmac_f32_e32 v89, v88, v88
	v_fmac_f32_e32 v92, v91, v91
	v_fmac_f32_e32 v94, v93, v93
	v_add_f32_e32 v86, v87, v89
	v_add_f32_e32 v87, v92, v94
	v_add_f32_e32 v86, v90, v86
	v_add_f32_e32 v86, v86, v87
	ds_swizzle_b32 v87, v86 offset:swizzle(SWAP,16)
	global_store_dwordx4 v[104:105], v[82:85], off offset:256
	s_waitcnt lgkmcnt(0)
	s_nop 0
	v_add_f32_e32 v82, v86, v87
	v_mov_b32_e32 v83, v82
	s_nop 1
	v_permlane32_swap_b32_e32 v82, v83
	s_and_saveexec_b64 s[54:55], vcc
	s_cbranch_execz .LBB0_1440
; __device__ __forceinline__ unsigned cvt_pk_bf16(float lo, float hi) { unsigned r; asm volatile("v_cvt_pk_bf16_f32 %0, %1, %2" : "=v"(r) : "v"(lo), "v"(hi)); return r; }
; __device__ __forceinline__ float bf_lo(unsigned w) { return __uint_as_float(w << 16); }
; __device__ __forceinline__ float bf_hi(unsigned w) { return __uint_as_float(w & 0xffff0000u); }
;     __device__ __forceinline__ void operator()(const f32x4 (&acc)[2][2][4][2], const Unit& u, int wr, int wc, int fr, int fq, const float (&rs)[2][4]) const {
;     ...
;             for (int m = 0; m < 4; ++m) { bf16_t* rowp = X + (size_t)(row0 + ai * HALF + m * 16) * DM + col0; float ss = 0.f;
; #pragma unroll
;                 for (int bj = 0; bj < 2; ++bj) { const u32x4 bw = *(const u32x4*)(rowp + bj * HALF); const f32x4 a0 = acc[ai][bj][m][0], a1 = acc[ai][bj][m][1];
;                     u32x4 w; w.x = cvt_pk_bf16(bf_lo(bw.x) + alpha * a0[0], bf_hi(bw.x) + alpha * a0[1]); w.y = cvt_pk_bf16(bf_lo(bw.y) + alpha * a0[2], bf_hi(bw.y) + alpha * a0[3]);
;                     w.z = cvt_pk_bf16(bf_lo(bw.z) + alpha * a1[0], bf_hi(bw.z) + alpha * a1[1]); w.w = cvt_pk_bf16(bf_lo(bw.w) + alpha * a1[2], bf_hi(bw.w) + alpha * a1[3]);
;                     *(u32x4*)(rowp + bj * HALF) = w;
;                     ss += (bf_lo(w.x) * bf_lo(w.x) + bf_hi(w.x) * bf_hi(w.x)) + (bf_lo(w.y) * bf_lo(w.y) + bf_hi(w.y) * bf_hi(w.y));
;                     ss += (bf_lo(w.z) * bf_lo(w.z) + bf_hi(w.z) * bf_hi(w.z)) + (bf_lo(w.w) * bf_lo(w.w) + bf_hi(w.w) * bf_hi(w.w)); }
;                 ss = fq_sum(ss);
;                 if (fq == 0) part[(size_t)(row0 + ai * HALF + m * 16) * 16 + u.pn * 4 + wc] = ss; } }
	v_lshlrev_b64 v[84:85], 6, v[98:99]
	v_lshl_add_u64 v[84:85], s[96:97], 0, v[84:85]
	v_lshl_add_u64 v[84:85], s[44:45], 2, v[84:85]
	s_lshl_b32 s58, s31, 2
	v_lshl_add_u64 v[84:85], v[84:85], 0, s[58:59]
	v_add_f32_e32 v82, v82, v83
	global_store_dword v[84:85], v82, off
.LBB0_1440:
	s_or_b64 exec, exec, s[54:55]
	v_add_u32_e32 v82, 48, v148
	v_ashrrev_i32_e32 v83, 31, v82
	v_lshlrev_b64 v[84:85], 11, v[82:83]
	v_lshl_add_u64 v[84:85], s[94:95], 0, v[84:85]
	v_lshl_add_u64 v[88:89], v[146:147], 1, v[84:85]
	s_nop 0
	s_waitcnt vmcnt(15)
	v_lshlrev_b32_e32 v90, 16, v206
	v_and_b32_e32 v84, 0xffff0000, v206
	v_lshlrev_b32_e32 v91, 16, v207
	v_and_b32_e32 v85, 0xffff0000, v207
	v_lshlrev_b32_e32 v93, 16, v209
	v_and_b32_e32 v87, 0xffff0000, v209
	v_lshlrev_b32_e32 v92, 16, v208
	v_and_b32_e32 v86, 0xffff0000, v208
	v_add_f32_e32 v76, v76, v90
	v_add_f32_e32 v77, v77, v84
	v_add_f32_e32 v78, v78, v91
	v_add_f32_e32 v79, v79, v85
	v_add_f32_e32 v75, v75, v87
	v_add_f32_e32 v84, v72, v92
	v_add_f32_e32 v85, v73, v86
	v_add_f32_e32 v86, v74, v93
	v_cvt_pk_bf16_f32 v72, v76, v77
	v_cvt_pk_bf16_f32 v73, v78, v79
	v_cvt_pk_bf16_f32 v74, v84, v85
	v_cvt_pk_bf16_f32 v75, v86, v75
	s_nop 0
	v_lshlrev_b32_e32 v84, 16, v72
	global_store_dwordx4 v[88:89], v[72:75], off
	v_lshlrev_b32_e32 v85, 16, v73
	v_lshlrev_b32_e32 v86, 16, v74
	v_and_b32_e32 v72, 0xffff0000, v72
	v_and_b32_e32 v73, 0xffff0000, v73
	v_and_b32_e32 v74, 0xffff0000, v74
	v_lshlrev_b32_e32 v87, 16, v75
	v_and_b32_e32 v75, 0xffff0000, v75
	v_mul_f32_e32 v72, v72, v72
	v_mul_f32_e32 v73, v73, v73
	v_mul_f32_e32 v74, v74, v74
	v_mul_f32_e32 v75, v75, v75
	v_fmac_f32_e32 v72, v84, v84
	v_fmac_f32_e32 v73, v85, v85
	v_fmac_f32_e32 v74, v86, v86
	v_fmac_f32_e32 v75, v87, v87
	v_add_f32_e32 v72, v72, v73
	v_add_f32_e32 v73, v74, v75
	v_add_f32_e32 v72, v72, v73
	s_waitcnt vmcnt(15)
	v_lshlrev_b32_e32 v73, 16, v210
	v_and_b32_e32 v74, 0xffff0000, v210
	v_and_b32_e32 v76, 0xffff0000, v211
	v_lshlrev_b32_e32 v75, 16, v211
	v_lshlrev_b32_e32 v77, 16, v212
	v_and_b32_e32 v78, 0xffff0000, v212
	v_lshlrev_b32_e32 v84, 16, v213
	v_and_b32_e32 v79, 0xffff0000, v213
	v_add_f32_e32 v69, v69, v74
	v_add_f32_e32 v71, v71, v76
	v_add_f32_e32 v68, v68, v73
	v_add_f32_e32 v70, v70, v75
	v_add_f32_e32 v73, v64, v77
	v_add_f32_e32 v74, v65, v78
	v_add_f32_e32 v67, v67, v79
	v_cvt_pk_bf16_f32 v64, v68, v69
	v_cvt_pk_bf16_f32 v65, v70, v71
	v_add_f32_e32 v75, v66, v84
	v_and_b32_e32 v69, 0xffff0000, v64
	v_and_b32_e32 v71, 0xffff0000, v65
	v_cvt_pk_bf16_f32 v66, v73, v74
	v_cvt_pk_bf16_f32 v67, v75, v67
	v_lshlrev_b32_e32 v68, 16, v64
	v_lshlrev_b32_e32 v70, 16, v65
	v_and_b32_e32 v74, 0xffff0000, v66
	v_and_b32_e32 v76, 0xffff0000, v67
	v_mul_f32_e32 v69, v69, v69
	v_mul_f32_e32 v71, v71, v71
	v_lshlrev_b32_e32 v73, 16, v66
	v_lshlrev_b32_e32 v75, 16, v67
	v_mul_f32_e32 v74, v74, v74
	v_mul_f32_e32 v76, v76, v76
	v_fmac_f32_e32 v69, v68, v68
	v_fmac_f32_e32 v71, v70, v70
	v_fmac_f32_e32 v74, v73, v73
	v_fmac_f32_e32 v76, v75, v75
	v_add_f32_e32 v68, v69, v71
	v_add_f32_e32 v69, v74, v76
	v_add_f32_e32 v68, v72, v68
	v_add_f32_e32 v68, v68, v69
	ds_swizzle_b32 v69, v68 offset:swizzle(SWAP,16)
	global_store_dwordx4 v[88:89], v[64:67], off offset:256
	s_waitcnt lgkmcnt(0)
	s_nop 0
	v_add_f32_e32 v64, v68, v69
	v_mov_b32_e32 v65, v64
	s_nop 1
	v_permlane32_swap_b32_e32 v64, v65
	s_and_saveexec_b64 s[54:55], vcc
	s_cbranch_execz .LBB0_1442
	v_lshlrev_b64 v[66:67], 6, v[82:83]
	v_lshl_add_u64 v[66:67], s[96:97], 0, v[66:67]
	v_lshl_add_u64 v[66:67], s[44:45], 2, v[66:67]
	s_lshl_b32 s58, s31, 2
	v_lshl_add_u64 v[66:67], v[66:67], 0, s[58:59]
	v_add_f32_e32 v64, v64, v65
	global_store_dword v[66:67], v64, off
.LBB0_1442:
	s_or_b64 exec, exec, s[54:55]
	v_add_u32_e32 v64, 0x80, v148
	v_ashrrev_i32_e32 v65, 31, v64
	v_lshlrev_b64 v[66:67], 11, v[64:65]
	v_lshl_add_u64 v[66:67], s[94:95], 0, v[66:67]
	v_lshl_add_u64 v[70:71], v[146:147], 1, v[66:67]
	s_nop 0
	s_waitcnt vmcnt(15)
	v_lshlrev_b32_e32 v72, 16, v214
	v_and_b32_e32 v66, 0xffff0000, v214
	v_lshlrev_b32_e32 v73, 16, v215
	v_and_b32_e32 v67, 0xffff0000, v215
	v_lshlrev_b32_e32 v75, 16, v217
	v_and_b32_e32 v69, 0xffff0000, v217
	v_lshlrev_b32_e32 v74, 16, v216
	v_and_b32_e32 v68, 0xffff0000, v216
	v_add_f32_e32 v60, v60, v72
	v_add_f32_e32 v61, v61, v66
	v_add_f32_e32 v62, v62, v73
	v_add_f32_e32 v63, v63, v67
	v_add_f32_e32 v59, v59, v69
	v_add_f32_e32 v66, v56, v74
	v_add_f32_e32 v67, v57, v68
	v_add_f32_e32 v68, v58, v75
	v_cvt_pk_bf16_f32 v56, v60, v61
	v_cvt_pk_bf16_f32 v57, v62, v63
	v_cvt_pk_bf16_f32 v58, v66, v67
	v_cvt_pk_bf16_f32 v59, v68, v59
	s_nop 0
	v_lshlrev_b32_e32 v66, 16, v56
	global_store_dwordx4 v[70:71], v[56:59], off
	v_lshlrev_b32_e32 v67, 16, v57
	v_lshlrev_b32_e32 v68, 16, v58
	v_and_b32_e32 v56, 0xffff0000, v56
	v_and_b32_e32 v57, 0xffff0000, v57
	v_and_b32_e32 v58, 0xffff0000, v58
	v_lshlrev_b32_e32 v69, 16, v59
	v_and_b32_e32 v59, 0xffff0000, v59
	v_mul_f32_e32 v56, v56, v56
	v_mul_f32_e32 v57, v57, v57
	v_mul_f32_e32 v58, v58, v58
	v_mul_f32_e32 v59, v59, v59
	v_fmac_f32_e32 v56, v66, v66
	v_fmac_f32_e32 v57, v67, v67
	v_fmac_f32_e32 v58, v68, v68
	v_fmac_f32_e32 v59, v69, v69
	v_add_f32_e32 v56, v56, v57
	v_add_f32_e32 v57, v58, v59
	v_add_f32_e32 v56, v56, v57
	s_waitcnt vmcnt(15)
	v_lshlrev_b32_e32 v57, 16, v218
	v_and_b32_e32 v58, 0xffff0000, v218
	v_and_b32_e32 v60, 0xffff0000, v219
	v_lshlrev_b32_e32 v59, 16, v219
	v_lshlrev_b32_e32 v61, 16, v220
	v_and_b32_e32 v62, 0xffff0000, v220
	v_lshlrev_b32_e32 v66, 16, v221
	v_and_b32_e32 v63, 0xffff0000, v221
	v_add_f32_e32 v53, v53, v58
	v_add_f32_e32 v55, v55, v60
	v_add_f32_e32 v52, v52, v57
	v_add_f32_e32 v54, v54, v59
	v_add_f32_e32 v57, v48, v61
	v_add_f32_e32 v58, v49, v62
	v_add_f32_e32 v51, v51, v63
	v_cvt_pk_bf16_f32 v48, v52, v53
	v_cvt_pk_bf16_f32 v49, v54, v55
	v_add_f32_e32 v59, v50, v66
	v_and_b32_e32 v53, 0xffff0000, v48
	v_and_b32_e32 v55, 0xffff0000, v49
	v_cvt_pk_bf16_f32 v50, v57, v58
	v_cvt_pk_bf16_f32 v51, v59, v51
	v_lshlrev_b32_e32 v52, 16, v48
	v_lshlrev_b32_e32 v54, 16, v49
	v_and_b32_e32 v58, 0xffff0000, v50
	v_and_b32_e32 v60, 0xffff0000, v51
	v_mul_f32_e32 v53, v53, v53
	v_mul_f32_e32 v55, v55, v55
	v_lshlrev_b32_e32 v57, 16, v50
	v_lshlrev_b32_e32 v59, 16, v51
	v_mul_f32_e32 v58, v58, v58
	v_mul_f32_e32 v60, v60, v60
	v_fmac_f32_e32 v53, v52, v52
	v_fmac_f32_e32 v55, v54, v54
	v_fmac_f32_e32 v58, v57, v57
	v_fmac_f32_e32 v60, v59, v59
	v_add_f32_e32 v52, v53, v55
	v_add_f32_e32 v53, v58, v60
	v_add_f32_e32 v52, v56, v52
	v_add_f32_e32 v52, v52, v53
	ds_swizzle_b32 v53, v52 offset:swizzle(SWAP,16)
	global_store_dwordx4 v[70:71], v[48:51], off offset:256
	s_waitcnt lgkmcnt(0)
	s_nop 0
	v_add_f32_e32 v48, v52, v53
	v_mov_b32_e32 v49, v48
	s_nop 1
	v_permlane32_swap_b32_e32 v48, v49
	s_and_saveexec_b64 s[54:55], vcc
	s_cbranch_execz .LBB0_1444
; __device__ __forceinline__ unsigned cvt_pk_bf16(float lo, float hi) { unsigned r; asm volatile("v_cvt_pk_bf16_f32 %0, %1, %2" : "=v"(r) : "v"(lo), "v"(hi)); return r; }
; __device__ __forceinline__ float bf_lo(unsigned w) { return __uint_as_float(w << 16); }
; __device__ __forceinline__ float bf_hi(unsigned w) { return __uint_as_float(w & 0xffff0000u); }
;     __device__ __forceinline__ void operator()(const f32x4 (&acc)[2][2][4][2], const Unit& u, int wr, int wc, int fr, int fq, const float (&rs)[2][4]) const {
;     ...
;             for (int m = 0; m < 4; ++m) { bf16_t* rowp = X + (size_t)(row0 + ai * HALF + m * 16) * DM + col0; float ss = 0.f;
; #pragma unroll
;                 for (int bj = 0; bj < 2; ++bj) { const u32x4 bw = *(const u32x4*)(rowp + bj * HALF); const f32x4 a0 = acc[ai][bj][m][0], a1 = acc[ai][bj][m][1];
;                     u32x4 w; w.x = cvt_pk_bf16(bf_lo(bw.x) + alpha * a0[0], bf_hi(bw.x) + alpha * a0[1]); w.y = cvt_pk_bf16(bf_lo(bw.y) + alpha * a0[2], bf_hi(bw.y) + alpha * a0[3]);
;                     w.z = cvt_pk_bf16(bf_lo(bw.z) + alpha * a1[0], bf_hi(bw.z) + alpha * a1[1]); w.w = cvt_pk_bf16(bf_lo(bw.w) + alpha * a1[2], bf_hi(bw.w) + alpha * a1[3]);
;                     *(u32x4*)(rowp + bj * HALF) = w;
;                     ss += (bf_lo(w.x) * bf_lo(w.x) + bf_hi(w.x) * bf_hi(w.x)) + (bf_lo(w.y) * bf_lo(w.y) + bf_hi(w.y) * bf_hi(w.y));
;                     ss += (bf_lo(w.z) * bf_lo(w.z) + bf_hi(w.z) * bf_hi(w.z)) + (bf_lo(w.w) * bf_lo(w.w) + bf_hi(w.w) * bf_hi(w.w)); }
;                 ss = fq_sum(ss);
;                 if (fq == 0) part[(size_t)(row0 + ai * HALF + m * 16) * 16 + u.pn * 4 + wc] = ss; } }
	v_lshlrev_b64 v[50:51], 6, v[64:65]
	v_lshl_add_u64 v[50:51], s[96:97], 0, v[50:51]
	v_lshl_add_u64 v[50:51], s[44:45], 2, v[50:51]
	s_lshl_b32 s58, s31, 2
	v_lshl_add_u64 v[50:51], v[50:51], 0, s[58:59]
	v_add_f32_e32 v48, v48, v49
	global_store_dword v[50:51], v48, off
.LBB0_1444:
	s_or_b64 exec, exec, s[54:55]
	v_add_u32_e32 v48, 0x90, v148
	v_ashrrev_i32_e32 v49, 31, v48
	v_lshlrev_b64 v[50:51], 11, v[48:49]
	v_lshl_add_u64 v[50:51], s[94:95], 0, v[50:51]
	v_lshl_add_u64 v[54:55], v[146:147], 1, v[50:51]
	s_nop 0
	s_waitcnt vmcnt(15)
	v_lshlrev_b32_e32 v56, 16, v222
	v_and_b32_e32 v50, 0xffff0000, v222
	v_lshlrev_b32_e32 v57, 16, v223
	v_and_b32_e32 v51, 0xffff0000, v223
	v_lshlrev_b32_e32 v59, 16, v225
	v_and_b32_e32 v53, 0xffff0000, v225
	v_lshlrev_b32_e32 v58, 16, v224
	v_and_b32_e32 v52, 0xffff0000, v224
	v_add_f32_e32 v44, v44, v56
	v_add_f32_e32 v45, v45, v50
	v_add_f32_e32 v46, v46, v57
	v_add_f32_e32 v47, v47, v51
	v_add_f32_e32 v43, v43, v53
	v_add_f32_e32 v50, v40, v58
	v_add_f32_e32 v51, v41, v52
	v_add_f32_e32 v52, v42, v59
	v_cvt_pk_bf16_f32 v40, v44, v45
	v_cvt_pk_bf16_f32 v41, v46, v47
	v_cvt_pk_bf16_f32 v42, v50, v51
	v_cvt_pk_bf16_f32 v43, v52, v43
	s_nop 0
	v_lshlrev_b32_e32 v50, 16, v40
	global_store_dwordx4 v[54:55], v[40:43], off
	v_lshlrev_b32_e32 v51, 16, v41
	v_lshlrev_b32_e32 v52, 16, v42
	v_and_b32_e32 v40, 0xffff0000, v40
	v_and_b32_e32 v41, 0xffff0000, v41
	v_and_b32_e32 v42, 0xffff0000, v42
	v_lshlrev_b32_e32 v53, 16, v43
	v_and_b32_e32 v43, 0xffff0000, v43
	v_mul_f32_e32 v40, v40, v40
	v_mul_f32_e32 v41, v41, v41
	v_mul_f32_e32 v42, v42, v42
	v_mul_f32_e32 v43, v43, v43
	v_fmac_f32_e32 v40, v50, v50
	v_fmac_f32_e32 v41, v51, v51
	v_fmac_f32_e32 v42, v52, v52
	v_fmac_f32_e32 v43, v53, v53
	v_add_f32_e32 v40, v40, v41
	v_add_f32_e32 v41, v42, v43
	v_add_f32_e32 v40, v40, v41
	s_waitcnt vmcnt(15)
	v_lshlrev_b32_e32 v41, 16, v226
	v_and_b32_e32 v42, 0xffff0000, v226
	v_and_b32_e32 v44, 0xffff0000, v227
	v_lshlrev_b32_e32 v43, 16, v227
	v_lshlrev_b32_e32 v45, 16, v228
	v_and_b32_e32 v46, 0xffff0000, v228
	v_lshlrev_b32_e32 v50, 16, v229
	v_and_b32_e32 v47, 0xffff0000, v229
	v_add_f32_e32 v37, v37, v42
	v_add_f32_e32 v39, v39, v44
	v_add_f32_e32 v36, v36, v41
	v_add_f32_e32 v38, v38, v43
	v_add_f32_e32 v41, v32, v45
	v_add_f32_e32 v42, v33, v46
	v_add_f32_e32 v35, v35, v47
	v_cvt_pk_bf16_f32 v32, v36, v37
	v_cvt_pk_bf16_f32 v33, v38, v39
	v_add_f32_e32 v43, v34, v50
	v_and_b32_e32 v37, 0xffff0000, v32
	v_and_b32_e32 v39, 0xffff0000, v33
	v_cvt_pk_bf16_f32 v34, v41, v42
	v_cvt_pk_bf16_f32 v35, v43, v35
	v_lshlrev_b32_e32 v36, 16, v32
	v_lshlrev_b32_e32 v38, 16, v33
	v_and_b32_e32 v42, 0xffff0000, v34
	v_and_b32_e32 v44, 0xffff0000, v35
	v_mul_f32_e32 v37, v37, v37
	v_mul_f32_e32 v39, v39, v39
	v_lshlrev_b32_e32 v41, 16, v34
	v_lshlrev_b32_e32 v43, 16, v35
	v_mul_f32_e32 v42, v42, v42
	v_mul_f32_e32 v44, v44, v44
	v_fmac_f32_e32 v37, v36, v36
	v_fmac_f32_e32 v39, v38, v38
	v_fmac_f32_e32 v42, v41, v41
	v_fmac_f32_e32 v44, v43, v43
	v_add_f32_e32 v36, v37, v39
	v_add_f32_e32 v37, v42, v44
	v_add_f32_e32 v36, v40, v36
	v_add_f32_e32 v36, v36, v37
	ds_swizzle_b32 v37, v36 offset:swizzle(SWAP,16)
	global_store_dwordx4 v[54:55], v[32:35], off offset:256
	s_waitcnt lgkmcnt(0)
	s_nop 0
	v_add_f32_e32 v32, v36, v37
	v_mov_b32_e32 v33, v32
	s_nop 1
	v_permlane32_swap_b32_e32 v32, v33
	s_and_saveexec_b64 s[54:55], vcc
	s_cbranch_execz .LBB0_1446
	v_lshlrev_b64 v[34:35], 6, v[48:49]
	v_lshl_add_u64 v[34:35], s[96:97], 0, v[34:35]
	v_lshl_add_u64 v[34:35], s[44:45], 2, v[34:35]
	s_lshl_b32 s58, s31, 2
	v_lshl_add_u64 v[34:35], v[34:35], 0, s[58:59]
	v_add_f32_e32 v32, v32, v33
	global_store_dword v[34:35], v32, off
; __device__ __forceinline__ unsigned cvt_pk_bf16(float lo, float hi) { unsigned r; asm volatile("v_cvt_pk_bf16_f32 %0, %1, %2" : "=v"(r) : "v"(lo), "v"(hi)); return r; }
; __device__ __forceinline__ float bf_lo(unsigned w) { return __uint_as_float(w << 16); }
; __device__ __forceinline__ float bf_hi(unsigned w) { return __uint_as_float(w & 0xffff0000u); }
;     __device__ __forceinline__ void operator()(const f32x4 (&acc)[2][2][4][2], const Unit& u, int wr, int wc, int fr, int fq, const float (&rs)[2][4]) const {
;     ...
;             for (int m = 0; m < 4; ++m) { bf16_t* rowp = X + (size_t)(row0 + ai * HALF + m * 16) * DM + col0; float ss = 0.f;
; #pragma unroll
;                 for (int bj = 0; bj < 2; ++bj) { const u32x4 bw = *(const u32x4*)(rowp + bj * HALF); const f32x4 a0 = acc[ai][bj][m][0], a1 = acc[ai][bj][m][1];
;                     u32x4 w; w.x = cvt_pk_bf16(bf_lo(bw.x) + alpha * a0[0], bf_hi(bw.x) + alpha * a0[1]); w.y = cvt_pk_bf16(bf_lo(bw.y) + alpha * a0[2], bf_hi(bw.y) + alpha * a0[3]);
;                     w.z = cvt_pk_bf16(bf_lo(bw.z) + alpha * a1[0], bf_hi(bw.z) + alpha * a1[1]); w.w = cvt_pk_bf16(bf_lo(bw.w) + alpha * a1[2], bf_hi(bw.w) + alpha * a1[3]);
;                     *(u32x4*)(rowp + bj * HALF) = w;
;                     ss += (bf_lo(w.x) * bf_lo(w.x) + bf_hi(w.x) * bf_hi(w.x)) + (bf_lo(w.y) * bf_lo(w.y) + bf_hi(w.y) * bf_hi(w.y));
;                     ss += (bf_lo(w.z) * bf_lo(w.z) + bf_hi(w.z) * bf_hi(w.z)) + (bf_lo(w.w) * bf_lo(w.w) + bf_hi(w.w) * bf_hi(w.w)); }
;                 ss = fq_sum(ss);
;                 if (fq == 0) part[(size_t)(row0 + ai * HALF + m * 16) * 16 + u.pn * 4 + wc] = ss; } }
.LBB0_1446:
	s_or_b64 exec, exec, s[54:55]
	v_add_u32_e32 v32, 0xa0, v148
	v_ashrrev_i32_e32 v33, 31, v32
	v_lshlrev_b64 v[34:35], 11, v[32:33]
	v_lshl_add_u64 v[34:35], s[94:95], 0, v[34:35]
	v_lshl_add_u64 v[38:39], v[146:147], 1, v[34:35]
	s_nop 0
	s_waitcnt vmcnt(15)
	v_lshlrev_b32_e32 v40, 16, v230
	v_and_b32_e32 v34, 0xffff0000, v230
	v_lshlrev_b32_e32 v41, 16, v231
	v_and_b32_e32 v35, 0xffff0000, v231
	v_lshlrev_b32_e32 v43, 16, v233
	v_and_b32_e32 v37, 0xffff0000, v233
	v_lshlrev_b32_e32 v42, 16, v232
	v_and_b32_e32 v36, 0xffff0000, v232
	v_add_f32_e32 v28, v28, v40
	v_add_f32_e32 v29, v29, v34
	v_add_f32_e32 v30, v30, v41
	v_add_f32_e32 v31, v31, v35
	v_add_f32_e32 v27, v27, v37
	v_add_f32_e32 v34, v24, v42
	v_add_f32_e32 v35, v25, v36
	v_add_f32_e32 v36, v26, v43
	v_cvt_pk_bf16_f32 v24, v28, v29
	v_cvt_pk_bf16_f32 v25, v30, v31
	v_cvt_pk_bf16_f32 v26, v34, v35
	v_cvt_pk_bf16_f32 v27, v36, v27
	s_nop 0
	v_lshlrev_b32_e32 v34, 16, v24
	global_store_dwordx4 v[38:39], v[24:27], off
	v_lshlrev_b32_e32 v35, 16, v25
	v_lshlrev_b32_e32 v36, 16, v26
	v_and_b32_e32 v24, 0xffff0000, v24
	v_and_b32_e32 v25, 0xffff0000, v25
	v_and_b32_e32 v26, 0xffff0000, v26
	v_lshlrev_b32_e32 v37, 16, v27
	v_and_b32_e32 v27, 0xffff0000, v27
	v_mul_f32_e32 v24, v24, v24
	v_mul_f32_e32 v25, v25, v25
	v_mul_f32_e32 v26, v26, v26
	v_mul_f32_e32 v27, v27, v27
	v_fmac_f32_e32 v24, v34, v34
	v_fmac_f32_e32 v25, v35, v35
	v_fmac_f32_e32 v26, v36, v36
	v_fmac_f32_e32 v27, v37, v37
	v_add_f32_e32 v24, v24, v25
	v_add_f32_e32 v25, v26, v27
	v_add_f32_e32 v24, v24, v25
	s_waitcnt vmcnt(15)
	v_lshlrev_b32_e32 v25, 16, v234
	v_and_b32_e32 v26, 0xffff0000, v234
	v_and_b32_e32 v28, 0xffff0000, v235
	v_lshlrev_b32_e32 v27, 16, v235
	v_lshlrev_b32_e32 v29, 16, v236
	v_and_b32_e32 v30, 0xffff0000, v236
	v_lshlrev_b32_e32 v34, 16, v237
	v_and_b32_e32 v31, 0xffff0000, v237
	v_add_f32_e32 v21, v21, v26
	v_add_f32_e32 v23, v23, v28
	v_add_f32_e32 v20, v20, v25
	v_add_f32_e32 v22, v22, v27
	v_add_f32_e32 v25, v16, v29
	v_add_f32_e32 v26, v17, v30
	v_add_f32_e32 v19, v19, v31
	v_cvt_pk_bf16_f32 v16, v20, v21
	v_cvt_pk_bf16_f32 v17, v22, v23
	v_add_f32_e32 v27, v18, v34
	v_and_b32_e32 v21, 0xffff0000, v16
	v_and_b32_e32 v23, 0xffff0000, v17
	v_cvt_pk_bf16_f32 v18, v25, v26
	v_cvt_pk_bf16_f32 v19, v27, v19
	v_lshlrev_b32_e32 v20, 16, v16
	v_lshlrev_b32_e32 v22, 16, v17
	v_and_b32_e32 v26, 0xffff0000, v18
	v_and_b32_e32 v28, 0xffff0000, v19
	v_mul_f32_e32 v21, v21, v21
	v_mul_f32_e32 v23, v23, v23
	v_lshlrev_b32_e32 v25, 16, v18
	v_lshlrev_b32_e32 v27, 16, v19
	v_mul_f32_e32 v26, v26, v26
	v_mul_f32_e32 v28, v28, v28
	v_fmac_f32_e32 v21, v20, v20
	v_fmac_f32_e32 v23, v22, v22
	v_fmac_f32_e32 v26, v25, v25
	v_fmac_f32_e32 v28, v27, v27
	v_add_f32_e32 v20, v21, v23
	v_add_f32_e32 v21, v26, v28
	v_add_f32_e32 v20, v24, v20
	v_add_f32_e32 v20, v20, v21
	ds_swizzle_b32 v21, v20 offset:swizzle(SWAP,16)
	global_store_dwordx4 v[38:39], v[16:19], off offset:256
	s_waitcnt lgkmcnt(0)
	s_nop 0
	v_add_f32_e32 v16, v20, v21
	v_mov_b32_e32 v17, v16
	s_nop 1
	v_permlane32_swap_b32_e32 v16, v17
	s_and_saveexec_b64 s[54:55], vcc
	s_cbranch_execz .LBB0_1448
	v_lshlrev_b64 v[18:19], 6, v[32:33]
	v_lshl_add_u64 v[18:19], s[96:97], 0, v[18:19]
	v_lshl_add_u64 v[18:19], s[44:45], 2, v[18:19]
	s_lshl_b32 s58, s31, 2
	v_lshl_add_u64 v[18:19], v[18:19], 0, s[58:59]
	v_add_f32_e32 v16, v16, v17
	global_store_dword v[18:19], v16, off
.LBB0_1448:
	s_or_b64 exec, exec, s[54:55]
	v_add_u32_e32 v16, 0xb0, v148
	v_ashrrev_i32_e32 v17, 31, v16
	v_lshlrev_b64 v[18:19], 11, v[16:17]
	v_lshl_add_u64 v[18:19], s[94:95], 0, v[18:19]
	v_lshl_add_u64 v[22:23], v[146:147], 1, v[18:19]
	s_nop 0
	s_waitcnt vmcnt(15)
	v_lshlrev_b32_e32 v24, 16, v238
	v_and_b32_e32 v18, 0xffff0000, v238
	v_lshlrev_b32_e32 v25, 16, v239
	v_and_b32_e32 v19, 0xffff0000, v239
	v_lshlrev_b32_e32 v27, 16, v241
	v_and_b32_e32 v21, 0xffff0000, v241
	v_lshlrev_b32_e32 v26, 16, v240
	v_and_b32_e32 v20, 0xffff0000, v240
	v_add_f32_e32 v12, v12, v24
	v_add_f32_e32 v13, v13, v18
	v_add_f32_e32 v14, v14, v25
	v_add_f32_e32 v15, v15, v19
	v_add_f32_e32 v11, v11, v21
	v_add_f32_e32 v18, v8, v26
	v_add_f32_e32 v19, v9, v20
	v_add_f32_e32 v20, v10, v27
	v_cvt_pk_bf16_f32 v8, v12, v13
	v_cvt_pk_bf16_f32 v9, v14, v15
	v_cvt_pk_bf16_f32 v10, v18, v19
	v_cvt_pk_bf16_f32 v11, v20, v11
	s_nop 0
	v_lshlrev_b32_e32 v18, 16, v8
	global_store_dwordx4 v[22:23], v[8:11], off
	v_lshlrev_b32_e32 v19, 16, v9
	v_lshlrev_b32_e32 v20, 16, v10
	v_and_b32_e32 v8, 0xffff0000, v8
	v_and_b32_e32 v9, 0xffff0000, v9
	v_and_b32_e32 v10, 0xffff0000, v10
	v_lshlrev_b32_e32 v21, 16, v11
	v_and_b32_e32 v11, 0xffff0000, v11
	v_mul_f32_e32 v8, v8, v8
	v_mul_f32_e32 v9, v9, v9
	v_mul_f32_e32 v10, v10, v10
	v_mul_f32_e32 v11, v11, v11
	v_fmac_f32_e32 v8, v18, v18
	v_fmac_f32_e32 v9, v19, v19
	v_fmac_f32_e32 v10, v20, v20
	v_fmac_f32_e32 v11, v21, v21
	v_add_f32_e32 v8, v8, v9
	v_add_f32_e32 v9, v10, v11
	v_add_f32_e32 v8, v8, v9
	s_waitcnt vmcnt(15)
	v_lshlrev_b32_e32 v9, 16, v242
	v_and_b32_e32 v10, 0xffff0000, v242
	v_and_b32_e32 v12, 0xffff0000, v243
	v_lshlrev_b32_e32 v11, 16, v243
	v_lshlrev_b32_e32 v13, 16, v244
	v_and_b32_e32 v14, 0xffff0000, v244
	v_lshlrev_b32_e32 v18, 16, v245
	v_and_b32_e32 v15, 0xffff0000, v245
	v_add_f32_e32 v5, v5, v10
	v_add_f32_e32 v7, v7, v12
	v_add_f32_e32 v4, v4, v9
	v_add_f32_e32 v6, v6, v11
	v_add_f32_e32 v9, v0, v13
	v_add_f32_e32 v10, v1, v14
	v_add_f32_e32 v3, v3, v15
	v_cvt_pk_bf16_f32 v0, v4, v5
	v_cvt_pk_bf16_f32 v1, v6, v7
	v_add_f32_e32 v11, v2, v18
	v_and_b32_e32 v5, 0xffff0000, v0
	v_and_b32_e32 v7, 0xffff0000, v1
	v_cvt_pk_bf16_f32 v2, v9, v10
	v_cvt_pk_bf16_f32 v3, v11, v3
	v_lshlrev_b32_e32 v4, 16, v0
	v_lshlrev_b32_e32 v6, 16, v1
	v_and_b32_e32 v10, 0xffff0000, v2
	v_and_b32_e32 v12, 0xffff0000, v3
	v_mul_f32_e32 v5, v5, v5
	v_mul_f32_e32 v7, v7, v7
	v_lshlrev_b32_e32 v9, 16, v2
	v_lshlrev_b32_e32 v11, 16, v3
	v_mul_f32_e32 v10, v10, v10
	v_mul_f32_e32 v12, v12, v12
	v_fmac_f32_e32 v5, v4, v4
	v_fmac_f32_e32 v7, v6, v6
	v_fmac_f32_e32 v10, v9, v9
	v_fmac_f32_e32 v12, v11, v11
	v_add_f32_e32 v4, v5, v7
	v_add_f32_e32 v5, v10, v12
	v_add_f32_e32 v4, v8, v4
	v_add_f32_e32 v4, v4, v5
	ds_swizzle_b32 v5, v4 offset:swizzle(SWAP,16)
	global_store_dwordx4 v[22:23], v[0:3], off offset:256
	s_waitcnt lgkmcnt(0)
	s_nop 0
	v_add_f32_e32 v0, v4, v5
	v_mov_b32_e32 v1, v0
	s_nop 1
	v_permlane32_swap_b32_e32 v0, v1
	s_and_saveexec_b64 s[54:55], vcc
	s_cbranch_execz .LBB0_1450
	v_lshlrev_b64 v[2:3], 6, v[16:17]
	v_lshl_add_u64 v[2:3], s[96:97], 0, v[2:3]
	v_lshl_add_u64 v[2:3], s[44:45], 2, v[2:3]
	s_lshl_b32 s58, s31, 2
	v_lshl_add_u64 v[2:3], v[2:3], 0, s[58:59]
	v_add_f32_e32 v0, v0, v1
	global_store_dword v[2:3], v0, off

; __device__ __forceinline__ unsigned cvt_pk_bf16(float lo, float hi) { unsigned r; asm volatile("v_cvt_pk_bf16_f32 %0, %1, %2" : "=v"(r) : "v"(lo), "v"(hi)); return r; }
; __device__ __forceinline__ float bf_lo(unsigned w) { return __uint_as_float(w << 16); }
; __device__ __forceinline__ float bf_hi(unsigned w) { return __uint_as_float(w & 0xffff0000u); }
;     __device__ __forceinline__ void operator()(const f32x4 (&acc)[2][2][4][2], const Unit& u, int wr, int wc, int fr, int fq, const float (&rs)[2][4]) const {
;     ...
;         const int row0 = u.pm * BM + wr * 64 + fr, col0 = u.pn * BM + wc * 32 + 8 * fq;
; #pragma unroll
;         for (int ai = 0; ai < 2; ++ai) {
; #pragma unroll
;             for (int m = 0; m < 4; ++m) { bf16_t* rowp = X + (size_t)(row0 + ai * HALF + m * 16) * DM + col0; float ss = 0.f;
; #pragma unroll
;                 for (int bj = 0; bj < 2; ++bj) { const u32x4 bw = *(const u32x4*)(rowp + bj * HALF); const f32x4 a0 = acc[ai][bj][m][0], a1 = acc[ai][bj][m][1];
;                     u32x4 w; w.x = cvt_pk_bf16(bf_lo(bw.x) + alpha * a0[0], bf_hi(bw.x) + alpha * a0[1]); w.y = cvt_pk_bf16(bf_lo(bw.y) + alpha * a0[2], bf_hi(bw.y) + alpha * a0[3]);
;                     w.z = cvt_pk_bf16(bf_lo(bw.z) + alpha * a1[0], bf_hi(bw.z) + alpha * a1[1]); w.w = cvt_pk_bf16(bf_lo(bw.w) + alpha * a1[2], bf_hi(bw.w) + alpha * a1[3]);
;                     *(u32x4*)(rowp + bj * HALF) = w;
;                     ss += (bf_lo(w.x) * bf_lo(w.x) + bf_hi(w.x) * bf_hi(w.x)) + (bf_lo(w.y) * bf_lo(w.y) + bf_hi(w.y) * bf_hi(w.y));
;                     ss += (bf_lo(w.z) * bf_lo(w.z) + bf_hi(w.z) * bf_hi(w.z)) + (bf_lo(w.w) * bf_lo(w.w) + bf_hi(w.w) * bf_hi(w.w)); }
;                 ss = fq_sum(ss);
;                 if (fq == 0) part[(size_t)(row0 + ai * HALF + m * 16) * 16 + u.pn * 4 + wc] = ss; } }
.LBB0_2018:
	s_lshl_b32 s0, s58, 8
	v_mov_b32_e32 v130, v151
	v_mov_b32_e32 v131, v150
	s_add_i32 s0, s0, s61
	s_lshl_b32 s42, s52, 2
	v_add_u32_e32 v148, s0, v130
	s_lshl_b32 s0, s52, 8
	s_or_b32 s0, s0, s66
	v_ashrrev_i32_e32 v149, 31, v148
	v_lshl_add_u32 v146, v131, 3, s0
	v_lshlrev_b64 v[154:155], 11, v[148:149]
	v_ashrrev_i32_e32 v147, 31, v146
	v_lshl_add_u64 v[154:155], s[94:95], 0, v[154:155]
	v_lshl_add_u64 v[158:159], v[146:147], 1, v[154:155]
	global_load_dwordx4 v[182:185], v[158:159], off
	global_load_dwordx4 v[186:189], v[158:159], off offset:256
	v_add_u32_e32 v246, 16, v148
	v_ashrrev_i32_e32 v247, 31, v246
	v_lshlrev_b64 v[246:247], 11, v[246:247]
	v_lshl_add_u64 v[246:247], s[94:95], 0, v[246:247]
	v_lshl_add_u64 v[246:247], v[146:147], 1, v[246:247]
	global_load_dwordx4 v[190:193], v[246:247], off
	global_load_dwordx4 v[194:197], v[246:247], off offset:256
	v_add_u32_e32 v248, 32, v148
	v_ashrrev_i32_e32 v249, 31, v248
	v_lshlrev_b64 v[248:249], 11, v[248:249]
	v_lshl_add_u64 v[248:249], s[94:95], 0, v[248:249]
	v_lshl_add_u64 v[248:249], v[146:147], 1, v[248:249]
	global_load_dwordx4 v[198:201], v[248:249], off
	global_load_dwordx4 v[202:205], v[248:249], off offset:256
	v_add_u32_e32 v246, 48, v148
	v_ashrrev_i32_e32 v247, 31, v246
	v_lshlrev_b64 v[246:247], 11, v[246:247]
	v_lshl_add_u64 v[246:247], s[94:95], 0, v[246:247]
	v_lshl_add_u64 v[246:247], v[146:147], 1, v[246:247]
	global_load_dwordx4 v[206:209], v[246:247], off
	global_load_dwordx4 v[210:213], v[246:247], off offset:256
	v_add_u32_e32 v248, 0x80, v148
	v_ashrrev_i32_e32 v249, 31, v248
	v_lshlrev_b64 v[248:249], 11, v[248:249]
	v_lshl_add_u64 v[248:249], s[94:95], 0, v[248:249]
	v_lshl_add_u64 v[248:249], v[146:147], 1, v[248:249]
	global_load_dwordx4 v[214:217], v[248:249], off
	global_load_dwordx4 v[218:221], v[248:249], off offset:256
	v_add_u32_e32 v246, 0x90, v148
	v_ashrrev_i32_e32 v247, 31, v246
	v_lshlrev_b64 v[246:247], 11, v[246:247]
	v_lshl_add_u64 v[246:247], s[94:95], 0, v[246:247]
	v_lshl_add_u64 v[246:247], v[146:147], 1, v[246:247]
	global_load_dwordx4 v[222:225], v[246:247], off
	global_load_dwordx4 v[226:229], v[246:247], off offset:256
	v_add_u32_e32 v248, 0xa0, v148
	v_ashrrev_i32_e32 v249, 31, v248
	v_lshlrev_b64 v[248:249], 11, v[248:249]
	v_lshl_add_u64 v[248:249], s[94:95], 0, v[248:249]
	v_lshl_add_u64 v[248:249], v[146:147], 1, v[248:249]
	global_load_dwordx4 v[230:233], v[248:249], off
	global_load_dwordx4 v[234:237], v[248:249], off offset:256
	v_add_u32_e32 v246, 0xb0, v148
	v_ashrrev_i32_e32 v247, 31, v246
	v_lshlrev_b64 v[246:247], 11, v[246:247]
	v_lshl_add_u64 v[246:247], s[94:95], 0, v[246:247]
	v_lshl_add_u64 v[246:247], v[146:147], 1, v[246:247]
	global_load_dwordx4 v[238:241], v[246:247], off
	global_load_dwordx4 v[242:245], v[246:247], off offset:256
	s_ashr_i32 s43, s42, 31
	v_cmp_eq_u32_e32 vcc, 0, v131
	s_waitcnt vmcnt(15)
	v_lshlrev_b32_e32 v130, 16, v182
	v_and_b32_e32 v134, 0xffff0000, v182
	v_lshlrev_b32_e32 v135, 16, v183
	v_and_b32_e32 v154, 0xffff0000, v183
	v_lshlrev_b32_e32 v160, 16, v185
	v_and_b32_e32 v157, 0xffff0000, v185
	v_lshlrev_b32_e32 v155, 16, v184
	v_and_b32_e32 v156, 0xffff0000, v184
	v_add_f32_e32 v126, v126, v130
	v_add_f32_e32 v127, v127, v134
	v_add_f32_e32 v128, v128, v135
	v_add_f32_e32 v129, v129, v154
	v_add_f32_e32 v125, v125, v157
	v_add_f32_e32 v130, v122, v155
	v_add_f32_e32 v134, v123, v156
	v_add_f32_e32 v135, v124, v160
	v_cvt_pk_bf16_f32 v122, v126, v127
	v_cvt_pk_bf16_f32 v123, v128, v129
	v_cvt_pk_bf16_f32 v124, v130, v134
	v_cvt_pk_bf16_f32 v125, v135, v125
	s_nop 0
	v_lshlrev_b32_e32 v130, 16, v122
	global_store_dwordx4 v[158:159], v[122:125], off
	v_lshlrev_b32_e32 v134, 16, v123
	v_lshlrev_b32_e32 v135, 16, v124
	v_and_b32_e32 v122, 0xffff0000, v122
	v_and_b32_e32 v123, 0xffff0000, v123
	v_and_b32_e32 v124, 0xffff0000, v124
	v_lshlrev_b32_e32 v154, 16, v125
	v_and_b32_e32 v125, 0xffff0000, v125
	v_mul_f32_e32 v122, v122, v122
	v_mul_f32_e32 v123, v123, v123
	v_mul_f32_e32 v124, v124, v124
	v_mul_f32_e32 v125, v125, v125
	v_fmac_f32_e32 v122, v130, v130
	v_fmac_f32_e32 v123, v134, v134
	v_fmac_f32_e32 v124, v135, v135
	v_fmac_f32_e32 v125, v154, v154
	v_add_f32_e32 v122, v122, v123
	v_add_f32_e32 v123, v124, v125
	v_add_f32_e32 v122, v122, v123
	s_waitcnt vmcnt(15)
	v_lshlrev_b32_e32 v123, 16, v186
	v_and_b32_e32 v124, 0xffff0000, v186
	v_and_b32_e32 v126, 0xffff0000, v187
	v_lshlrev_b32_e32 v125, 16, v187
	v_lshlrev_b32_e32 v127, 16, v188
	v_and_b32_e32 v128, 0xffff0000, v188
	v_lshlrev_b32_e32 v130, 16, v189
	v_and_b32_e32 v129, 0xffff0000, v189
	v_add_f32_e32 v119, v119, v124
	v_add_f32_e32 v121, v121, v126
	v_add_f32_e32 v118, v118, v123
	v_add_f32_e32 v120, v120, v125
	v_add_f32_e32 v123, v114, v127
	v_add_f32_e32 v124, v115, v128
	v_add_f32_e32 v117, v117, v129
	v_cvt_pk_bf16_f32 v114, v118, v119
	v_cvt_pk_bf16_f32 v115, v120, v121
	v_add_f32_e32 v125, v116, v130
	v_and_b32_e32 v119, 0xffff0000, v114
	v_and_b32_e32 v121, 0xffff0000, v115
	v_cvt_pk_bf16_f32 v116, v123, v124
	v_cvt_pk_bf16_f32 v117, v125, v117
	v_lshlrev_b32_e32 v118, 16, v114
	v_lshlrev_b32_e32 v120, 16, v115
	v_and_b32_e32 v124, 0xffff0000, v116
	v_and_b32_e32 v126, 0xffff0000, v117
	v_mul_f32_e32 v119, v119, v119
	v_mul_f32_e32 v121, v121, v121
	v_lshlrev_b32_e32 v123, 16, v116
	v_lshlrev_b32_e32 v125, 16, v117
	v_mul_f32_e32 v124, v124, v124
	v_mul_f32_e32 v126, v126, v126
	v_fmac_f32_e32 v119, v118, v118
	v_fmac_f32_e32 v121, v120, v120
	v_fmac_f32_e32 v124, v123, v123
	v_fmac_f32_e32 v126, v125, v125
	v_add_f32_e32 v118, v119, v121
	v_add_f32_e32 v119, v124, v126
	v_add_f32_e32 v118, v122, v118
	v_add_f32_e32 v118, v118, v119
	ds_swizzle_b32 v119, v118 offset:swizzle(SWAP,16)
	global_store_dwordx4 v[158:159], v[114:117], off offset:256
	s_waitcnt lgkmcnt(0)
	s_nop 0
	v_add_f32_e32 v114, v118, v119
	v_mov_b32_e32 v115, v114
	s_nop 1
	v_permlane32_swap_b32_e32 v114, v115
	s_and_saveexec_b64 s[52:53], vcc
	s_cbranch_execz .LBB0_2020
	v_lshlrev_b64 v[116:117], 6, v[148:149]
	v_lshl_add_u64 v[116:117], s[96:97], 0, v[116:117]
	v_lshl_add_u64 v[116:117], s[42:43], 2, v[116:117]
	s_lshl_b32 s58, s31, 2
	v_lshl_add_u64 v[116:117], v[116:117], 0, s[58:59]
	v_add_f32_e32 v114, v114, v115
	global_store_dword v[116:117], v114, off
; __device__ __forceinline__ unsigned cvt_pk_bf16(float lo, float hi) { unsigned r; asm volatile("v_cvt_pk_bf16_f32 %0, %1, %2" : "=v"(r) : "v"(lo), "v"(hi)); return r; }
; __device__ __forceinline__ float bf_lo(unsigned w) { return __uint_as_float(w << 16); }
; __device__ __forceinline__ float bf_hi(unsigned w) { return __uint_as_float(w & 0xffff0000u); }
;     __device__ __forceinline__ void operator()(const f32x4 (&acc)[2][2][4][2], const Unit& u, int wr, int wc, int fr, int fq, const float (&rs)[2][4]) const {
;     ...
;             for (int m = 0; m < 4; ++m) { bf16_t* rowp = X + (size_t)(row0 + ai * HALF + m * 16) * DM + col0; float ss = 0.f;
; #pragma unroll
;                 for (int bj = 0; bj < 2; ++bj) { const u32x4 bw = *(const u32x4*)(rowp + bj * HALF); const f32x4 a0 = acc[ai][bj][m][0], a1 = acc[ai][bj][m][1];
;                     u32x4 w; w.x = cvt_pk_bf16(bf_lo(bw.x) + alpha * a0[0], bf_hi(bw.x) + alpha * a0[1]); w.y = cvt_pk_bf16(bf_lo(bw.y) + alpha * a0[2], bf_hi(bw.y) + alpha * a0[3]);
;                     w.z = cvt_pk_bf16(bf_lo(bw.z) + alpha * a1[0], bf_hi(bw.z) + alpha * a1[1]); w.w = cvt_pk_bf16(bf_lo(bw.w) + alpha * a1[2], bf_hi(bw.w) + alpha * a1[3]);
;                     *(u32x4*)(rowp + bj * HALF) = w;
;                     ss += (bf_lo(w.x) * bf_lo(w.x) + bf_hi(w.x) * bf_hi(w.x)) + (bf_lo(w.y) * bf_lo(w.y) + bf_hi(w.y) * bf_hi(w.y));
;                     ss += (bf_lo(w.z) * bf_lo(w.z) + bf_hi(w.z) * bf_hi(w.z)) + (bf_lo(w.w) * bf_lo(w.w) + bf_hi(w.w) * bf_hi(w.w)); }
;                 ss = fq_sum(ss);
;                 if (fq == 0) part[(size_t)(row0 + ai * HALF + m * 16) * 16 + u.pn * 4 + wc] = ss; } }
.LBB0_2020:
	s_or_b64 exec, exec, s[52:53]
	v_add_u32_e32 v114, 16, v148
	v_ashrrev_i32_e32 v115, 31, v114
	v_lshlrev_b64 v[116:117], 11, v[114:115]
	v_lshl_add_u64 v[116:117], s[94:95], 0, v[116:117]
	v_lshl_add_u64 v[120:121], v[146:147], 1, v[116:117]
	s_nop 0
	s_waitcnt vmcnt(15)
	v_lshlrev_b32_e32 v122, 16, v190
	v_and_b32_e32 v116, 0xffff0000, v190
	v_lshlrev_b32_e32 v123, 16, v191
	v_and_b32_e32 v117, 0xffff0000, v191
	v_lshlrev_b32_e32 v125, 16, v193
	v_and_b32_e32 v119, 0xffff0000, v193
	v_lshlrev_b32_e32 v124, 16, v192
	v_and_b32_e32 v118, 0xffff0000, v192
	v_add_f32_e32 v110, v110, v122
	v_add_f32_e32 v111, v111, v116
	v_add_f32_e32 v112, v112, v123
	v_add_f32_e32 v113, v113, v117
	v_add_f32_e32 v109, v109, v119
	v_add_f32_e32 v116, v106, v124
	v_add_f32_e32 v117, v107, v118
	v_add_f32_e32 v118, v108, v125
	v_cvt_pk_bf16_f32 v106, v110, v111
	v_cvt_pk_bf16_f32 v107, v112, v113
	v_cvt_pk_bf16_f32 v108, v116, v117
	v_cvt_pk_bf16_f32 v109, v118, v109
	s_nop 0
	v_lshlrev_b32_e32 v116, 16, v106
	global_store_dwordx4 v[120:121], v[106:109], off
	v_lshlrev_b32_e32 v117, 16, v107
	v_lshlrev_b32_e32 v118, 16, v108
	v_and_b32_e32 v106, 0xffff0000, v106
	v_and_b32_e32 v107, 0xffff0000, v107
	v_and_b32_e32 v108, 0xffff0000, v108
	v_lshlrev_b32_e32 v119, 16, v109
	v_and_b32_e32 v109, 0xffff0000, v109
	v_mul_f32_e32 v106, v106, v106
	v_mul_f32_e32 v107, v107, v107
	v_mul_f32_e32 v108, v108, v108
	v_mul_f32_e32 v109, v109, v109
	v_fmac_f32_e32 v106, v116, v116
	v_fmac_f32_e32 v107, v117, v117
	v_fmac_f32_e32 v108, v118, v118
	v_fmac_f32_e32 v109, v119, v119
	v_add_f32_e32 v106, v106, v107
	v_add_f32_e32 v107, v108, v109
	v_add_f32_e32 v106, v106, v107
	s_waitcnt vmcnt(15)
	v_lshlrev_b32_e32 v107, 16, v194
	v_and_b32_e32 v108, 0xffff0000, v194
	v_and_b32_e32 v110, 0xffff0000, v195
	v_lshlrev_b32_e32 v109, 16, v195
	v_lshlrev_b32_e32 v111, 16, v196
	v_and_b32_e32 v112, 0xffff0000, v196
	v_lshlrev_b32_e32 v116, 16, v197
	v_and_b32_e32 v113, 0xffff0000, v197
	v_add_f32_e32 v103, v103, v108
	v_add_f32_e32 v105, v105, v110
	v_add_f32_e32 v102, v102, v107
	v_add_f32_e32 v104, v104, v109
	v_add_f32_e32 v107, v98, v111
	v_add_f32_e32 v108, v99, v112
	v_add_f32_e32 v101, v101, v113
	v_cvt_pk_bf16_f32 v98, v102, v103
	v_cvt_pk_bf16_f32 v99, v104, v105
	v_add_f32_e32 v109, v100, v116
	v_and_b32_e32 v103, 0xffff0000, v98
	v_and_b32_e32 v105, 0xffff0000, v99
	v_cvt_pk_bf16_f32 v100, v107, v108
	v_cvt_pk_bf16_f32 v101, v109, v101
	v_lshlrev_b32_e32 v102, 16, v98
	v_lshlrev_b32_e32 v104, 16, v99
	v_and_b32_e32 v108, 0xffff0000, v100
	v_and_b32_e32 v110, 0xffff0000, v101
	v_mul_f32_e32 v103, v103, v103
	v_mul_f32_e32 v105, v105, v105
	v_lshlrev_b32_e32 v107, 16, v100
	v_lshlrev_b32_e32 v109, 16, v101
	v_mul_f32_e32 v108, v108, v108
	v_mul_f32_e32 v110, v110, v110
	v_fmac_f32_e32 v103, v102, v102
	v_fmac_f32_e32 v105, v104, v104
	v_fmac_f32_e32 v108, v107, v107
	v_fmac_f32_e32 v110, v109, v109
	v_add_f32_e32 v102, v103, v105
	v_add_f32_e32 v103, v108, v110
	v_add_f32_e32 v102, v106, v102
	v_add_f32_e32 v102, v102, v103
	ds_swizzle_b32 v103, v102 offset:swizzle(SWAP,16)
	global_store_dwordx4 v[120:121], v[98:101], off offset:256
	s_waitcnt lgkmcnt(0)
	s_nop 0
	v_add_f32_e32 v98, v102, v103
	v_mov_b32_e32 v99, v98
	s_nop 1
	v_permlane32_swap_b32_e32 v98, v99
	s_and_saveexec_b64 s[52:53], vcc
	s_cbranch_execz .LBB0_2022
	v_lshlrev_b64 v[100:101], 6, v[114:115]
	v_lshl_add_u64 v[100:101], s[96:97], 0, v[100:101]
	v_lshl_add_u64 v[100:101], s[42:43], 2, v[100:101]
	s_lshl_b32 s58, s31, 2
	v_lshl_add_u64 v[100:101], v[100:101], 0, s[58:59]
	v_add_f32_e32 v98, v98, v99
	global_store_dword v[100:101], v98, off
.LBB0_2022:
	s_or_b64 exec, exec, s[52:53]
	v_add_u32_e32 v98, 32, v148
	v_ashrrev_i32_e32 v99, 31, v98
	v_lshlrev_b64 v[100:101], 11, v[98:99]
	v_lshl_add_u64 v[100:101], s[94:95], 0, v[100:101]
	v_lshl_add_u64 v[104:105], v[146:147], 1, v[100:101]
	s_nop 0
	s_waitcnt vmcnt(15)
	v_lshlrev_b32_e32 v106, 16, v198
	v_and_b32_e32 v100, 0xffff0000, v198
	v_lshlrev_b32_e32 v107, 16, v199
	v_and_b32_e32 v101, 0xffff0000, v199
	v_lshlrev_b32_e32 v109, 16, v201
	v_and_b32_e32 v103, 0xffff0000, v201
	v_lshlrev_b32_e32 v108, 16, v200
	v_and_b32_e32 v102, 0xffff0000, v200
	v_add_f32_e32 v94, v94, v106
	v_add_f32_e32 v95, v95, v100
	v_add_f32_e32 v96, v96, v107
	v_add_f32_e32 v97, v97, v101
	v_add_f32_e32 v93, v93, v103
	v_add_f32_e32 v100, v90, v108
	v_add_f32_e32 v101, v91, v102
	v_add_f32_e32 v102, v92, v109
	v_cvt_pk_bf16_f32 v90, v94, v95
	v_cvt_pk_bf16_f32 v91, v96, v97
	v_cvt_pk_bf16_f32 v92, v100, v101
	v_cvt_pk_bf16_f32 v93, v102, v93
	s_nop 0
	v_lshlrev_b32_e32 v100, 16, v90
	global_store_dwordx4 v[104:105], v[90:93], off
	v_lshlrev_b32_e32 v101, 16, v91
	v_lshlrev_b32_e32 v102, 16, v92
	v_and_b32_e32 v90, 0xffff0000, v90
	v_and_b32_e32 v91, 0xffff0000, v91
	v_and_b32_e32 v92, 0xffff0000, v92
	v_lshlrev_b32_e32 v103, 16, v93
	v_and_b32_e32 v93, 0xffff0000, v93
	v_mul_f32_e32 v90, v90, v90
	v_mul_f32_e32 v91, v91, v91
	v_mul_f32_e32 v92, v92, v92
	v_mul_f32_e32 v93, v93, v93
	v_fmac_f32_e32 v90, v100, v100
	v_fmac_f32_e32 v91, v101, v101
	v_fmac_f32_e32 v92, v102, v102
	v_fmac_f32_e32 v93, v103, v103
	v_add_f32_e32 v90, v90, v91
	v_add_f32_e32 v91, v92, v93
	v_add_f32_e32 v90, v90, v91
	s_waitcnt vmcnt(15)
	v_lshlrev_b32_e32 v91, 16, v202
	v_and_b32_e32 v92, 0xffff0000, v202
	v_and_b32_e32 v94, 0xffff0000, v203
	v_lshlrev_b32_e32 v93, 16, v203
	v_lshlrev_b32_e32 v95, 16, v204
	v_and_b32_e32 v96, 0xffff0000, v204
	v_lshlrev_b32_e32 v100, 16, v205
	v_and_b32_e32 v97, 0xffff0000, v205
	v_add_f32_e32 v87, v87, v92
	v_add_f32_e32 v89, v89, v94
	v_add_f32_e32 v86, v86, v91
	v_add_f32_e32 v88, v88, v93
	v_add_f32_e32 v91, v82, v95
	v_add_f32_e32 v92, v83, v96
	v_add_f32_e32 v85, v85, v97
	v_cvt_pk_bf16_f32 v82, v86, v87
	v_cvt_pk_bf16_f32 v83, v88, v89
	v_add_f32_e32 v93, v84, v100
	v_and_b32_e32 v87, 0xffff0000, v82
	v_and_b32_e32 v89, 0xffff0000, v83
	v_cvt_pk_bf16_f32 v84, v91, v92
	v_cvt_pk_bf16_f32 v85, v93, v85
	v_lshlrev_b32_e32 v86, 16, v82
	v_lshlrev_b32_e32 v88, 16, v83
	v_and_b32_e32 v92, 0xffff0000, v84
	v_and_b32_e32 v94, 0xffff0000, v85
	v_mul_f32_e32 v87, v87, v87
	v_mul_f32_e32 v89, v89, v89
	v_lshlrev_b32_e32 v91, 16, v84
	v_lshlrev_b32_e32 v93, 16, v85
	v_mul_f32_e32 v92, v92, v92
	v_mul_f32_e32 v94, v94, v94
	v_fmac_f32_e32 v87, v86, v86
	v_fmac_f32_e32 v89, v88, v88
	v_fmac_f32_e32 v92, v91, v91
	v_fmac_f32_e32 v94, v93, v93
	v_add_f32_e32 v86, v87, v89
	v_add_f32_e32 v87, v92, v94
	v_add_f32_e32 v86, v90, v86
	v_add_f32_e32 v86, v86, v87
	ds_swizzle_b32 v87, v86 offset:swizzle(SWAP,16)
	global_store_dwordx4 v[104:105], v[82:85], off offset:256
	s_waitcnt lgkmcnt(0)
	s_nop 0
	v_add_f32_e32 v82, v86, v87
	v_mov_b32_e32 v83, v82
	s_nop 1
	v_permlane32_swap_b32_e32 v82, v83
	s_and_saveexec_b64 s[52:53], vcc
	s_cbranch_execz .LBB0_2024
; __device__ __forceinline__ unsigned cvt_pk_bf16(float lo, float hi) { unsigned r; asm volatile("v_cvt_pk_bf16_f32 %0, %1, %2" : "=v"(r) : "v"(lo), "v"(hi)); return r; }
; __device__ __forceinline__ float bf_lo(unsigned w) { return __uint_as_float(w << 16); }
; __device__ __forceinline__ float bf_hi(unsigned w) { return __uint_as_float(w & 0xffff0000u); }
;     __device__ __forceinline__ void operator()(const f32x4 (&acc)[2][2][4][2], const Unit& u, int wr, int wc, int fr, int fq, const float (&rs)[2][4]) const {
;     ...
;             for (int m = 0; m < 4; ++m) { bf16_t* rowp = X + (size_t)(row0 + ai * HALF + m * 16) * DM + col0; float ss = 0.f;
; #pragma unroll
;                 for (int bj = 0; bj < 2; ++bj) { const u32x4 bw = *(const u32x4*)(rowp + bj * HALF); const f32x4 a0 = acc[ai][bj][m][0], a1 = acc[ai][bj][m][1];
;                     u32x4 w; w.x = cvt_pk_bf16(bf_lo(bw.x) + alpha * a0[0], bf_hi(bw.x) + alpha * a0[1]); w.y = cvt_pk_bf16(bf_lo(bw.y) + alpha * a0[2], bf_hi(bw.y) + alpha * a0[3]);
;                     w.z = cvt_pk_bf16(bf_lo(bw.z) + alpha * a1[0], bf_hi(bw.z) + alpha * a1[1]); w.w = cvt_pk_bf16(bf_lo(bw.w) + alpha * a1[2], bf_hi(bw.w) + alpha * a1[3]);
;                     *(u32x4*)(rowp + bj * HALF) = w;
;                     ss += (bf_lo(w.x) * bf_lo(w.x) + bf_hi(w.x) * bf_hi(w.x)) + (bf_lo(w.y) * bf_lo(w.y) + bf_hi(w.y) * bf_hi(w.y));
;                     ss += (bf_lo(w.z) * bf_lo(w.z) + bf_hi(w.z) * bf_hi(w.z)) + (bf_lo(w.w) * bf_lo(w.w) + bf_hi(w.w) * bf_hi(w.w)); }
;                 ss = fq_sum(ss);
;                 if (fq == 0) part[(size_t)(row0 + ai * HALF + m * 16) * 16 + u.pn * 4 + wc] = ss; } }
	v_lshlrev_b64 v[84:85], 6, v[98:99]
	v_lshl_add_u64 v[84:85], s[96:97], 0, v[84:85]
	v_lshl_add_u64 v[84:85], s[42:43], 2, v[84:85]
	s_lshl_b32 s58, s31, 2
	v_lshl_add_u64 v[84:85], v[84:85], 0, s[58:59]
	v_add_f32_e32 v82, v82, v83
	global_store_dword v[84:85], v82, off
.LBB0_2024:
	s_or_b64 exec, exec, s[52:53]
	v_add_u32_e32 v82, 48, v148
	v_ashrrev_i32_e32 v83, 31, v82
	v_lshlrev_b64 v[84:85], 11, v[82:83]
	v_lshl_add_u64 v[84:85], s[94:95], 0, v[84:85]
	v_lshl_add_u64 v[88:89], v[146:147], 1, v[84:85]
	s_nop 0
	s_waitcnt vmcnt(15)
	v_lshlrev_b32_e32 v90, 16, v206
	v_and_b32_e32 v84, 0xffff0000, v206
	v_lshlrev_b32_e32 v91, 16, v207
	v_and_b32_e32 v85, 0xffff0000, v207
	v_lshlrev_b32_e32 v93, 16, v209
	v_and_b32_e32 v87, 0xffff0000, v209
	v_lshlrev_b32_e32 v92, 16, v208
	v_and_b32_e32 v86, 0xffff0000, v208
	v_add_f32_e32 v76, v76, v90
	v_add_f32_e32 v77, v77, v84
	v_add_f32_e32 v78, v78, v91
	v_add_f32_e32 v79, v79, v85
	v_add_f32_e32 v75, v75, v87
	v_add_f32_e32 v84, v72, v92
	v_add_f32_e32 v85, v73, v86
	v_add_f32_e32 v86, v74, v93
	v_cvt_pk_bf16_f32 v72, v76, v77
	v_cvt_pk_bf16_f32 v73, v78, v79
	v_cvt_pk_bf16_f32 v74, v84, v85
	v_cvt_pk_bf16_f32 v75, v86, v75
	s_nop 0
	v_lshlrev_b32_e32 v84, 16, v72
	global_store_dwordx4 v[88:89], v[72:75], off
	v_lshlrev_b32_e32 v85, 16, v73
	v_lshlrev_b32_e32 v86, 16, v74
	v_and_b32_e32 v72, 0xffff0000, v72
	v_and_b32_e32 v73, 0xffff0000, v73
	v_and_b32_e32 v74, 0xffff0000, v74
	v_lshlrev_b32_e32 v87, 16, v75
	v_and_b32_e32 v75, 0xffff0000, v75
	v_mul_f32_e32 v72, v72, v72
	v_mul_f32_e32 v73, v73, v73
	v_mul_f32_e32 v74, v74, v74
	v_mul_f32_e32 v75, v75, v75
	v_fmac_f32_e32 v72, v84, v84
	v_fmac_f32_e32 v73, v85, v85
	v_fmac_f32_e32 v74, v86, v86
	v_fmac_f32_e32 v75, v87, v87
	v_add_f32_e32 v72, v72, v73
	v_add_f32_e32 v73, v74, v75
	v_add_f32_e32 v72, v72, v73
	s_waitcnt vmcnt(15)
	v_lshlrev_b32_e32 v73, 16, v210
	v_and_b32_e32 v74, 0xffff0000, v210
	v_and_b32_e32 v76, 0xffff0000, v211
	v_lshlrev_b32_e32 v75, 16, v211
	v_lshlrev_b32_e32 v77, 16, v212
	v_and_b32_e32 v78, 0xffff0000, v212
	v_lshlrev_b32_e32 v84, 16, v213
	v_and_b32_e32 v79, 0xffff0000, v213
	v_add_f32_e32 v69, v69, v74
	v_add_f32_e32 v71, v71, v76
	v_add_f32_e32 v68, v68, v73
	v_add_f32_e32 v70, v70, v75
	v_add_f32_e32 v73, v64, v77
	v_add_f32_e32 v74, v65, v78
	v_add_f32_e32 v67, v67, v79
	v_cvt_pk_bf16_f32 v64, v68, v69
	v_cvt_pk_bf16_f32 v65, v70, v71
	v_add_f32_e32 v75, v66, v84
	v_and_b32_e32 v69, 0xffff0000, v64
	v_and_b32_e32 v71, 0xffff0000, v65
	v_cvt_pk_bf16_f32 v66, v73, v74
	v_cvt_pk_bf16_f32 v67, v75, v67
	v_lshlrev_b32_e32 v68, 16, v64
	v_lshlrev_b32_e32 v70, 16, v65
	v_and_b32_e32 v74, 0xffff0000, v66
	v_and_b32_e32 v76, 0xffff0000, v67
	v_mul_f32_e32 v69, v69, v69
	v_mul_f32_e32 v71, v71, v71
	v_lshlrev_b32_e32 v73, 16, v66
	v_lshlrev_b32_e32 v75, 16, v67
	v_mul_f32_e32 v74, v74, v74
	v_mul_f32_e32 v76, v76, v76
	v_fmac_f32_e32 v69, v68, v68
	v_fmac_f32_e32 v71, v70, v70
	v_fmac_f32_e32 v74, v73, v73
	v_fmac_f32_e32 v76, v75, v75
	v_add_f32_e32 v68, v69, v71
	v_add_f32_e32 v69, v74, v76
	v_add_f32_e32 v68, v72, v68
	v_add_f32_e32 v68, v68, v69
	ds_swizzle_b32 v69, v68 offset:swizzle(SWAP,16)
	global_store_dwordx4 v[88:89], v[64:67], off offset:256
	s_waitcnt lgkmcnt(0)
	s_nop 0
	v_add_f32_e32 v64, v68, v69
	v_mov_b32_e32 v65, v64
	s_nop 1
	v_permlane32_swap_b32_e32 v64, v65
	s_and_saveexec_b64 s[52:53], vcc
	s_cbranch_execz .LBB0_2026
	v_lshlrev_b64 v[66:67], 6, v[82:83]
	v_lshl_add_u64 v[66:67], s[96:97], 0, v[66:67]
	v_lshl_add_u64 v[66:67], s[42:43], 2, v[66:67]
	s_lshl_b32 s58, s31, 2
	v_lshl_add_u64 v[66:67], v[66:67], 0, s[58:59]
	v_add_f32_e32 v64, v64, v65
	global_store_dword v[66:67], v64, off
.LBB0_2026:
	s_or_b64 exec, exec, s[52:53]
	v_add_u32_e32 v64, 0x80, v148
	v_ashrrev_i32_e32 v65, 31, v64
	v_lshlrev_b64 v[66:67], 11, v[64:65]
	v_lshl_add_u64 v[66:67], s[94:95], 0, v[66:67]
	v_lshl_add_u64 v[70:71], v[146:147], 1, v[66:67]
	s_nop 0
	s_waitcnt vmcnt(15)
	v_lshlrev_b32_e32 v72, 16, v214
	v_and_b32_e32 v66, 0xffff0000, v214
	v_lshlrev_b32_e32 v73, 16, v215
	v_and_b32_e32 v67, 0xffff0000, v215
	v_lshlrev_b32_e32 v75, 16, v217
	v_and_b32_e32 v69, 0xffff0000, v217
	v_lshlrev_b32_e32 v74, 16, v216
	v_and_b32_e32 v68, 0xffff0000, v216
	v_add_f32_e32 v60, v60, v72
	v_add_f32_e32 v61, v61, v66
	v_add_f32_e32 v62, v62, v73
	v_add_f32_e32 v63, v63, v67
	v_add_f32_e32 v59, v59, v69
	v_add_f32_e32 v66, v56, v74
	v_add_f32_e32 v67, v57, v68
	v_add_f32_e32 v68, v58, v75
	v_cvt_pk_bf16_f32 v56, v60, v61
	v_cvt_pk_bf16_f32 v57, v62, v63
	v_cvt_pk_bf16_f32 v58, v66, v67
	v_cvt_pk_bf16_f32 v59, v68, v59
	s_nop 0
	v_lshlrev_b32_e32 v66, 16, v56
	global_store_dwordx4 v[70:71], v[56:59], off
	v_lshlrev_b32_e32 v67, 16, v57
	v_lshlrev_b32_e32 v68, 16, v58
	v_and_b32_e32 v56, 0xffff0000, v56
	v_and_b32_e32 v57, 0xffff0000, v57
	v_and_b32_e32 v58, 0xffff0000, v58
	v_lshlrev_b32_e32 v69, 16, v59
	v_and_b32_e32 v59, 0xffff0000, v59
	v_mul_f32_e32 v56, v56, v56
	v_mul_f32_e32 v57, v57, v57
	v_mul_f32_e32 v58, v58, v58
	v_mul_f32_e32 v59, v59, v59
	v_fmac_f32_e32 v56, v66, v66
	v_fmac_f32_e32 v57, v67, v67
	v_fmac_f32_e32 v58, v68, v68
	v_fmac_f32_e32 v59, v69, v69
	v_add_f32_e32 v56, v56, v57
	v_add_f32_e32 v57, v58, v59
	v_add_f32_e32 v56, v56, v57
	s_waitcnt vmcnt(15)
	v_lshlrev_b32_e32 v57, 16, v218
	v_and_b32_e32 v58, 0xffff0000, v218
	v_and_b32_e32 v60, 0xffff0000, v219
	v_lshlrev_b32_e32 v59, 16, v219
	v_lshlrev_b32_e32 v61, 16, v220
	v_and_b32_e32 v62, 0xffff0000, v220
	v_lshlrev_b32_e32 v66, 16, v221
	v_and_b32_e32 v63, 0xffff0000, v221
	v_add_f32_e32 v53, v53, v58
	v_add_f32_e32 v55, v55, v60
	v_add_f32_e32 v52, v52, v57
	v_add_f32_e32 v54, v54, v59
	v_add_f32_e32 v57, v48, v61
	v_add_f32_e32 v58, v49, v62
	v_add_f32_e32 v51, v51, v63
	v_cvt_pk_bf16_f32 v48, v52, v53
	v_cvt_pk_bf16_f32 v49, v54, v55
	v_add_f32_e32 v59, v50, v66
	v_and_b32_e32 v53, 0xffff0000, v48
	v_and_b32_e32 v55, 0xffff0000, v49
	v_cvt_pk_bf16_f32 v50, v57, v58
	v_cvt_pk_bf16_f32 v51, v59, v51
	v_lshlrev_b32_e32 v52, 16, v48
	v_lshlrev_b32_e32 v54, 16, v49
	v_and_b32_e32 v58, 0xffff0000, v50
	v_and_b32_e32 v60, 0xffff0000, v51
	v_mul_f32_e32 v53, v53, v53
	v_mul_f32_e32 v55, v55, v55
	v_lshlrev_b32_e32 v57, 16, v50
	v_lshlrev_b32_e32 v59, 16, v51
	v_mul_f32_e32 v58, v58, v58
	v_mul_f32_e32 v60, v60, v60
	v_fmac_f32_e32 v53, v52, v52
	v_fmac_f32_e32 v55, v54, v54
	v_fmac_f32_e32 v58, v57, v57
	v_fmac_f32_e32 v60, v59, v59
	v_add_f32_e32 v52, v53, v55
	v_add_f32_e32 v53, v58, v60
	v_add_f32_e32 v52, v56, v52
	v_add_f32_e32 v52, v52, v53
	ds_swizzle_b32 v53, v52 offset:swizzle(SWAP,16)
	global_store_dwordx4 v[70:71], v[48:51], off offset:256
	s_waitcnt lgkmcnt(0)
	s_nop 0
	v_add_f32_e32 v48, v52, v53
	v_mov_b32_e32 v49, v48
	s_nop 1
	v_permlane32_swap_b32_e32 v48, v49
	s_and_saveexec_b64 s[52:53], vcc
	s_cbranch_execz .LBB0_2028
; __device__ __forceinline__ unsigned cvt_pk_bf16(float lo, float hi) { unsigned r; asm volatile("v_cvt_pk_bf16_f32 %0, %1, %2" : "=v"(r) : "v"(lo), "v"(hi)); return r; }
; __device__ __forceinline__ float bf_lo(unsigned w) { return __uint_as_float(w << 16); }
; __device__ __forceinline__ float bf_hi(unsigned w) { return __uint_as_float(w & 0xffff0000u); }
;     __device__ __forceinline__ void operator()(const f32x4 (&acc)[2][2][4][2], const Unit& u, int wr, int wc, int fr, int fq, const float (&rs)[2][4]) const {
;     ...
;             for (int m = 0; m < 4; ++m) { bf16_t* rowp = X + (size_t)(row0 + ai * HALF + m * 16) * DM + col0; float ss = 0.f;
; #pragma unroll
;                 for (int bj = 0; bj < 2; ++bj) { const u32x4 bw = *(const u32x4*)(rowp + bj * HALF); const f32x4 a0 = acc[ai][bj][m][0], a1 = acc[ai][bj][m][1];
;                     u32x4 w; w.x = cvt_pk_bf16(bf_lo(bw.x) + alpha * a0[0], bf_hi(bw.x) + alpha * a0[1]); w.y = cvt_pk_bf16(bf_lo(bw.y) + alpha * a0[2], bf_hi(bw.y) + alpha * a0[3]);
;                     w.z = cvt_pk_bf16(bf_lo(bw.z) + alpha * a1[0], bf_hi(bw.z) + alpha * a1[1]); w.w = cvt_pk_bf16(bf_lo(bw.w) + alpha * a1[2], bf_hi(bw.w) + alpha * a1[3]);
;                     *(u32x4*)(rowp + bj * HALF) = w;
;                     ss += (bf_lo(w.x) * bf_lo(w.x) + bf_hi(w.x) * bf_hi(w.x)) + (bf_lo(w.y) * bf_lo(w.y) + bf_hi(w.y) * bf_hi(w.y));
;                     ss += (bf_lo(w.z) * bf_lo(w.z) + bf_hi(w.z) * bf_hi(w.z)) + (bf_lo(w.w) * bf_lo(w.w) + bf_hi(w.w) * bf_hi(w.w)); }
;                 ss = fq_sum(ss);
;                 if (fq == 0) part[(size_t)(row0 + ai * HALF + m * 16) * 16 + u.pn * 4 + wc] = ss; } }
	v_lshlrev_b64 v[50:51], 6, v[64:65]
	v_lshl_add_u64 v[50:51], s[96:97], 0, v[50:51]
	v_lshl_add_u64 v[50:51], s[42:43], 2, v[50:51]
	s_lshl_b32 s58, s31, 2
	v_lshl_add_u64 v[50:51], v[50:51], 0, s[58:59]
	v_add_f32_e32 v48, v48, v49
	global_store_dword v[50:51], v48, off
.LBB0_2028:
	s_or_b64 exec, exec, s[52:53]
	v_add_u32_e32 v48, 0x90, v148
	v_ashrrev_i32_e32 v49, 31, v48
	v_lshlrev_b64 v[50:51], 11, v[48:49]
	v_lshl_add_u64 v[50:51], s[94:95], 0, v[50:51]
	v_lshl_add_u64 v[54:55], v[146:147], 1, v[50:51]
	s_nop 0
	s_waitcnt vmcnt(15)
	v_lshlrev_b32_e32 v56, 16, v222
	v_and_b32_e32 v50, 0xffff0000, v222
	v_lshlrev_b32_e32 v57, 16, v223
	v_and_b32_e32 v51, 0xffff0000, v223
	v_lshlrev_b32_e32 v59, 16, v225
	v_and_b32_e32 v53, 0xffff0000, v225
	v_lshlrev_b32_e32 v58, 16, v224
	v_and_b32_e32 v52, 0xffff0000, v224
	v_add_f32_e32 v44, v44, v56
	v_add_f32_e32 v45, v45, v50
	v_add_f32_e32 v46, v46, v57
	v_add_f32_e32 v47, v47, v51
	v_add_f32_e32 v43, v43, v53
	v_add_f32_e32 v50, v40, v58
	v_add_f32_e32 v51, v41, v52
	v_add_f32_e32 v52, v42, v59
	v_cvt_pk_bf16_f32 v40, v44, v45
	v_cvt_pk_bf16_f32 v41, v46, v47
	v_cvt_pk_bf16_f32 v42, v50, v51
	v_cvt_pk_bf16_f32 v43, v52, v43
	s_nop 0
	v_lshlrev_b32_e32 v50, 16, v40
	global_store_dwordx4 v[54:55], v[40:43], off
	v_lshlrev_b32_e32 v51, 16, v41
	v_lshlrev_b32_e32 v52, 16, v42
	v_and_b32_e32 v40, 0xffff0000, v40
	v_and_b32_e32 v41, 0xffff0000, v41
	v_and_b32_e32 v42, 0xffff0000, v42
	v_lshlrev_b32_e32 v53, 16, v43
	v_and_b32_e32 v43, 0xffff0000, v43
	v_mul_f32_e32 v40, v40, v40
	v_mul_f32_e32 v41, v41, v41
	v_mul_f32_e32 v42, v42, v42
	v_mul_f32_e32 v43, v43, v43
	v_fmac_f32_e32 v40, v50, v50
	v_fmac_f32_e32 v41, v51, v51
	v_fmac_f32_e32 v42, v52, v52
	v_fmac_f32_e32 v43, v53, v53
	v_add_f32_e32 v40, v40, v41
	v_add_f32_e32 v41, v42, v43
	v_add_f32_e32 v40, v40, v41
	s_waitcnt vmcnt(15)
	v_lshlrev_b32_e32 v41, 16, v226
	v_and_b32_e32 v42, 0xffff0000, v226
	v_and_b32_e32 v44, 0xffff0000, v227
	v_lshlrev_b32_e32 v43, 16, v227
	v_lshlrev_b32_e32 v45, 16, v228
	v_and_b32_e32 v46, 0xffff0000, v228
	v_lshlrev_b32_e32 v50, 16, v229
	v_and_b32_e32 v47, 0xffff0000, v229
	v_add_f32_e32 v37, v37, v42
	v_add_f32_e32 v39, v39, v44
	v_add_f32_e32 v36, v36, v41
	v_add_f32_e32 v38, v38, v43
	v_add_f32_e32 v41, v32, v45
	v_add_f32_e32 v42, v33, v46
	v_add_f32_e32 v35, v35, v47
	v_cvt_pk_bf16_f32 v32, v36, v37
	v_cvt_pk_bf16_f32 v33, v38, v39
	v_add_f32_e32 v43, v34, v50
	v_and_b32_e32 v37, 0xffff0000, v32
	v_and_b32_e32 v39, 0xffff0000, v33
	v_cvt_pk_bf16_f32 v34, v41, v42
	v_cvt_pk_bf16_f32 v35, v43, v35
	v_lshlrev_b32_e32 v36, 16, v32
	v_lshlrev_b32_e32 v38, 16, v33
	v_and_b32_e32 v42, 0xffff0000, v34
	v_and_b32_e32 v44, 0xffff0000, v35
	v_mul_f32_e32 v37, v37, v37
	v_mul_f32_e32 v39, v39, v39
	v_lshlrev_b32_e32 v41, 16, v34
	v_lshlrev_b32_e32 v43, 16, v35
	v_mul_f32_e32 v42, v42, v42
	v_mul_f32_e32 v44, v44, v44
	v_fmac_f32_e32 v37, v36, v36
	v_fmac_f32_e32 v39, v38, v38
	v_fmac_f32_e32 v42, v41, v41
	v_fmac_f32_e32 v44, v43, v43
	v_add_f32_e32 v36, v37, v39
	v_add_f32_e32 v37, v42, v44
	v_add_f32_e32 v36, v40, v36
	v_add_f32_e32 v36, v36, v37
	ds_swizzle_b32 v37, v36 offset:swizzle(SWAP,16)
	global_store_dwordx4 v[54:55], v[32:35], off offset:256
	s_waitcnt lgkmcnt(0)
	s_nop 0
	v_add_f32_e32 v32, v36, v37
	v_mov_b32_e32 v33, v32
	s_nop 1
	v_permlane32_swap_b32_e32 v32, v33
	s_and_saveexec_b64 s[52:53], vcc
	s_cbranch_execz .LBB0_2030
	v_lshlrev_b64 v[34:35], 6, v[48:49]
	v_lshl_add_u64 v[34:35], s[96:97], 0, v[34:35]
	v_lshl_add_u64 v[34:35], s[42:43], 2, v[34:35]
	s_lshl_b32 s58, s31, 2
	v_lshl_add_u64 v[34:35], v[34:35], 0, s[58:59]
	v_add_f32_e32 v32, v32, v33
	global_store_dword v[34:35], v32, off
; __device__ __forceinline__ unsigned cvt_pk_bf16(float lo, float hi) { unsigned r; asm volatile("v_cvt_pk_bf16_f32 %0, %1, %2" : "=v"(r) : "v"(lo), "v"(hi)); return r; }
; __device__ __forceinline__ float bf_lo(unsigned w) { return __uint_as_float(w << 16); }
; __device__ __forceinline__ float bf_hi(unsigned w) { return __uint_as_float(w & 0xffff0000u); }
;     __device__ __forceinline__ void operator()(const f32x4 (&acc)[2][2][4][2], const Unit& u, int wr, int wc, int fr, int fq, const float (&rs)[2][4]) const {
;     ...
;             for (int m = 0; m < 4; ++m) { bf16_t* rowp = X + (size_t)(row0 + ai * HALF + m * 16) * DM + col0; float ss = 0.f;
; #pragma unroll
;                 for (int bj = 0; bj < 2; ++bj) { const u32x4 bw = *(const u32x4*)(rowp + bj * HALF); const f32x4 a0 = acc[ai][bj][m][0], a1 = acc[ai][bj][m][1];
;                     u32x4 w; w.x = cvt_pk_bf16(bf_lo(bw.x) + alpha * a0[0], bf_hi(bw.x) + alpha * a0[1]); w.y = cvt_pk_bf16(bf_lo(bw.y) + alpha * a0[2], bf_hi(bw.y) + alpha * a0[3]);
;                     w.z = cvt_pk_bf16(bf_lo(bw.z) + alpha * a1[0], bf_hi(bw.z) + alpha * a1[1]); w.w = cvt_pk_bf16(bf_lo(bw.w) + alpha * a1[2], bf_hi(bw.w) + alpha * a1[3]);
;                     *(u32x4*)(rowp + bj * HALF) = w;
;                     ss += (bf_lo(w.x) * bf_lo(w.x) + bf_hi(w.x) * bf_hi(w.x)) + (bf_lo(w.y) * bf_lo(w.y) + bf_hi(w.y) * bf_hi(w.y));
;                     ss += (bf_lo(w.z) * bf_lo(w.z) + bf_hi(w.z) * bf_hi(w.z)) + (bf_lo(w.w) * bf_lo(w.w) + bf_hi(w.w) * bf_hi(w.w)); }
;                 ss = fq_sum(ss);
;                 if (fq == 0) part[(size_t)(row0 + ai * HALF + m * 16) * 16 + u.pn * 4 + wc] = ss; } }
.LBB0_2030:
	s_or_b64 exec, exec, s[52:53]
	v_add_u32_e32 v32, 0xa0, v148
	v_ashrrev_i32_e32 v33, 31, v32
	v_lshlrev_b64 v[34:35], 11, v[32:33]
	v_lshl_add_u64 v[34:35], s[94:95], 0, v[34:35]
	v_lshl_add_u64 v[38:39], v[146:147], 1, v[34:35]
	s_nop 0
	s_waitcnt vmcnt(15)
	v_lshlrev_b32_e32 v40, 16, v230
	v_and_b32_e32 v34, 0xffff0000, v230
	v_lshlrev_b32_e32 v41, 16, v231
	v_and_b32_e32 v35, 0xffff0000, v231
	v_lshlrev_b32_e32 v43, 16, v233
	v_and_b32_e32 v37, 0xffff0000, v233
	v_lshlrev_b32_e32 v42, 16, v232
	v_and_b32_e32 v36, 0xffff0000, v232
	v_add_f32_e32 v28, v28, v40
	v_add_f32_e32 v29, v29, v34
	v_add_f32_e32 v30, v30, v41
	v_add_f32_e32 v31, v31, v35
	v_add_f32_e32 v27, v27, v37
	v_add_f32_e32 v34, v24, v42
	v_add_f32_e32 v35, v25, v36
	v_add_f32_e32 v36, v26, v43
	v_cvt_pk_bf16_f32 v24, v28, v29
	v_cvt_pk_bf16_f32 v25, v30, v31
	v_cvt_pk_bf16_f32 v26, v34, v35
	v_cvt_pk_bf16_f32 v27, v36, v27
	s_nop 0
	v_lshlrev_b32_e32 v34, 16, v24
	global_store_dwordx4 v[38:39], v[24:27], off
	v_lshlrev_b32_e32 v35, 16, v25
	v_lshlrev_b32_e32 v36, 16, v26
	v_and_b32_e32 v24, 0xffff0000, v24
	v_and_b32_e32 v25, 0xffff0000, v25
	v_and_b32_e32 v26, 0xffff0000, v26
	v_lshlrev_b32_e32 v37, 16, v27
	v_and_b32_e32 v27, 0xffff0000, v27
	v_mul_f32_e32 v24, v24, v24
	v_mul_f32_e32 v25, v25, v25
	v_mul_f32_e32 v26, v26, v26
	v_mul_f32_e32 v27, v27, v27
	v_fmac_f32_e32 v24, v34, v34
	v_fmac_f32_e32 v25, v35, v35
	v_fmac_f32_e32 v26, v36, v36
	v_fmac_f32_e32 v27, v37, v37
	v_add_f32_e32 v24, v24, v25
	v_add_f32_e32 v25, v26, v27
	v_add_f32_e32 v24, v24, v25
	s_waitcnt vmcnt(15)
	v_lshlrev_b32_e32 v25, 16, v234
	v_and_b32_e32 v26, 0xffff0000, v234
	v_and_b32_e32 v28, 0xffff0000, v235
	v_lshlrev_b32_e32 v27, 16, v235
	v_lshlrev_b32_e32 v29, 16, v236
	v_and_b32_e32 v30, 0xffff0000, v236
	v_lshlrev_b32_e32 v34, 16, v237
	v_and_b32_e32 v31, 0xffff0000, v237
	v_add_f32_e32 v21, v21, v26
	v_add_f32_e32 v23, v23, v28
	v_add_f32_e32 v20, v20, v25
	v_add_f32_e32 v22, v22, v27
	v_add_f32_e32 v25, v16, v29
	v_add_f32_e32 v26, v17, v30
	v_add_f32_e32 v19, v19, v31
	v_cvt_pk_bf16_f32 v16, v20, v21
	v_cvt_pk_bf16_f32 v17, v22, v23
	v_add_f32_e32 v27, v18, v34
	v_and_b32_e32 v21, 0xffff0000, v16
	v_and_b32_e32 v23, 0xffff0000, v17
	v_cvt_pk_bf16_f32 v18, v25, v26
	v_cvt_pk_bf16_f32 v19, v27, v19
	v_lshlrev_b32_e32 v20, 16, v16
	v_lshlrev_b32_e32 v22, 16, v17
	v_and_b32_e32 v26, 0xffff0000, v18
	v_and_b32_e32 v28, 0xffff0000, v19
	v_mul_f32_e32 v21, v21, v21
	v_mul_f32_e32 v23, v23, v23
	v_lshlrev_b32_e32 v25, 16, v18
	v_lshlrev_b32_e32 v27, 16, v19
	v_mul_f32_e32 v26, v26, v26
	v_mul_f32_e32 v28, v28, v28
	v_fmac_f32_e32 v21, v20, v20
	v_fmac_f32_e32 v23, v22, v22
	v_fmac_f32_e32 v26, v25, v25
	v_fmac_f32_e32 v28, v27, v27
	v_add_f32_e32 v20, v21, v23
	v_add_f32_e32 v21, v26, v28
	v_add_f32_e32 v20, v24, v20
	v_add_f32_e32 v20, v20, v21
	ds_swizzle_b32 v21, v20 offset:swizzle(SWAP,16)
	global_store_dwordx4 v[38:39], v[16:19], off offset:256
	s_waitcnt lgkmcnt(0)
	s_nop 0
	v_add_f32_e32 v16, v20, v21
	v_mov_b32_e32 v17, v16
	s_nop 1
	v_permlane32_swap_b32_e32 v16, v17
	s_and_saveexec_b64 s[52:53], vcc
	s_cbranch_execz .LBB0_2032
	v_lshlrev_b64 v[18:19], 6, v[32:33]
	v_lshl_add_u64 v[18:19], s[96:97], 0, v[18:19]
	v_lshl_add_u64 v[18:19], s[42:43], 2, v[18:19]
	s_lshl_b32 s58, s31, 2
	v_lshl_add_u64 v[18:19], v[18:19], 0, s[58:59]
	v_add_f32_e32 v16, v16, v17
	global_store_dword v[18:19], v16, off
.LBB0_2032:
	s_or_b64 exec, exec, s[52:53]
	v_add_u32_e32 v16, 0xb0, v148
	v_ashrrev_i32_e32 v17, 31, v16
	v_lshlrev_b64 v[18:19], 11, v[16:17]
	v_lshl_add_u64 v[18:19], s[94:95], 0, v[18:19]
	v_lshl_add_u64 v[22:23], v[146:147], 1, v[18:19]
	s_nop 0
	s_waitcnt vmcnt(15)
	v_lshlrev_b32_e32 v24, 16, v238
	v_and_b32_e32 v18, 0xffff0000, v238
	v_lshlrev_b32_e32 v25, 16, v239
	v_and_b32_e32 v19, 0xffff0000, v239
	v_lshlrev_b32_e32 v27, 16, v241
	v_and_b32_e32 v21, 0xffff0000, v241
	v_lshlrev_b32_e32 v26, 16, v240
	v_and_b32_e32 v20, 0xffff0000, v240
	v_add_f32_e32 v12, v12, v24
	v_add_f32_e32 v13, v13, v18
	v_add_f32_e32 v14, v14, v25
	v_add_f32_e32 v15, v15, v19
	v_add_f32_e32 v11, v11, v21
	v_add_f32_e32 v18, v8, v26
	v_add_f32_e32 v19, v9, v20
	v_add_f32_e32 v20, v10, v27
	v_cvt_pk_bf16_f32 v8, v12, v13
	v_cvt_pk_bf16_f32 v9, v14, v15
	v_cvt_pk_bf16_f32 v10, v18, v19
	v_cvt_pk_bf16_f32 v11, v20, v11
	s_nop 0
	v_lshlrev_b32_e32 v18, 16, v8
	global_store_dwordx4 v[22:23], v[8:11], off
	v_lshlrev_b32_e32 v19, 16, v9
	v_lshlrev_b32_e32 v20, 16, v10
	v_and_b32_e32 v8, 0xffff0000, v8
	v_and_b32_e32 v9, 0xffff0000, v9
	v_and_b32_e32 v10, 0xffff0000, v10
	v_lshlrev_b32_e32 v21, 16, v11
	v_and_b32_e32 v11, 0xffff0000, v11
	v_mul_f32_e32 v8, v8, v8
	v_mul_f32_e32 v9, v9, v9
	v_mul_f32_e32 v10, v10, v10
	v_mul_f32_e32 v11, v11, v11
	v_fmac_f32_e32 v8, v18, v18
	v_fmac_f32_e32 v9, v19, v19
	v_fmac_f32_e32 v10, v20, v20
	v_fmac_f32_e32 v11, v21, v21
	v_add_f32_e32 v8, v8, v9
	v_add_f32_e32 v9, v10, v11
	v_add_f32_e32 v8, v8, v9
	s_waitcnt vmcnt(15)
	v_lshlrev_b32_e32 v9, 16, v242
	v_and_b32_e32 v10, 0xffff0000, v242
	v_and_b32_e32 v12, 0xffff0000, v243
	v_lshlrev_b32_e32 v11, 16, v243
	v_lshlrev_b32_e32 v13, 16, v244
	v_and_b32_e32 v14, 0xffff0000, v244
	v_lshlrev_b32_e32 v18, 16, v245
	v_and_b32_e32 v15, 0xffff0000, v245
	v_add_f32_e32 v5, v5, v10
	v_add_f32_e32 v7, v7, v12
	v_add_f32_e32 v4, v4, v9
	v_add_f32_e32 v6, v6, v11
	v_add_f32_e32 v9, v0, v13
	v_add_f32_e32 v10, v1, v14
	v_add_f32_e32 v3, v3, v15
	v_cvt_pk_bf16_f32 v0, v4, v5
	v_cvt_pk_bf16_f32 v1, v6, v7
	v_add_f32_e32 v11, v2, v18
	v_and_b32_e32 v5, 0xffff0000, v0
	v_and_b32_e32 v7, 0xffff0000, v1
	v_cvt_pk_bf16_f32 v2, v9, v10
	v_cvt_pk_bf16_f32 v3, v11, v3
	v_lshlrev_b32_e32 v4, 16, v0
	v_lshlrev_b32_e32 v6, 16, v1
	v_and_b32_e32 v10, 0xffff0000, v2
	v_and_b32_e32 v12, 0xffff0000, v3
	v_mul_f32_e32 v5, v5, v5
	v_mul_f32_e32 v7, v7, v7
	v_lshlrev_b32_e32 v9, 16, v2
	v_lshlrev_b32_e32 v11, 16, v3
	v_mul_f32_e32 v10, v10, v10
	v_mul_f32_e32 v12, v12, v12
	v_fmac_f32_e32 v5, v4, v4
	v_fmac_f32_e32 v7, v6, v6
	v_fmac_f32_e32 v10, v9, v9
	v_fmac_f32_e32 v12, v11, v11
	v_add_f32_e32 v4, v5, v7
	v_add_f32_e32 v5, v10, v12
	v_add_f32_e32 v4, v8, v4
	v_add_f32_e32 v4, v4, v5
	ds_swizzle_b32 v5, v4 offset:swizzle(SWAP,16)
	global_store_dwordx4 v[22:23], v[0:3], off offset:256
	s_waitcnt lgkmcnt(0)
	s_nop 0
	v_add_f32_e32 v0, v4, v5
	v_mov_b32_e32 v1, v0
	s_nop 1
	v_permlane32_swap_b32_e32 v0, v1
	s_and_saveexec_b64 s[52:53], vcc
	s_cbranch_execz .LBB0_2034
	v_lshlrev_b64 v[2:3], 6, v[16:17]
	v_lshl_add_u64 v[2:3], s[96:97], 0, v[2:3]
	v_lshl_add_u64 v[2:3], s[42:43], 2, v[2:3]
	s_lshl_b32 s58, s31, 2
	v_lshl_add_u64 v[2:3], v[2:3], 0, s[58:59]
	v_add_f32_e32 v0, v0, v1
	global_store_dword v[2:3], v0, off
